# GEMM K-loops: 8 of the 16 LDS-DMA loads per iteration issued in SGPR-base + 32-bit lane offset form (single-use v_lshl_add_u64 deleted), on top of MLA saddr
# speedup vs baseline: 1.0214x; 1.0013x over previous
.LBB0_266:
	ds_read_b128 v[152:155], v166
	ds_read_b128 v[156:159], v166 offset:1024
	ds_read_b128 v[172:175], v166 offset:2048
	ds_read_b128 v[176:179], v166 offset:3072
	ds_read_b128 v[180:183], v167
	ds_read_b128 v[184:187], v167 offset:1024
	ds_read_b128 v[188:191], v167 offset:2048
	ds_read_b128 v[192:195], v167 offset:3072
	s_add_u32 s62, s8, 0xfff80080
	s_addc_u32 s63, s9, -1
	s_cmp_eq_u32 s74, 28
	s_cselect_b32 s65, s11, s63
	s_cselect_b32 s64, s12, s62
	s_cselect_b32 s63, s13, s61
	s_cselect_b32 s62, s45, s49
	s_add_i32 m0, s79, 0xc000
	ds_read_b128 v[196:199], v168
	ds_read_b128 v[200:203], v168 offset:1024
	ds_read_b128 v[204:207], v168 offset:2048
	ds_read_b128 v[208:211], v168 offset:3072
	ds_read_b128 v[212:215], v168 offset:4096
	ds_read_b128 v[216:219], v168 offset:5120
	ds_read_b128 v[220:223], v168 offset:6144
	ds_read_b128 v[224:227], v168 offset:7168
	global_load_lds_dwordx4 v142, s[8:9]
	s_add_i32 m0, s79, 0xe000
	s_nop 0
	global_load_lds_dwordx4 v144, s[8:9]
	s_waitcnt vmcnt(8)
	s_waitcnt lgkmcnt(0)
	s_barrier
	s_setprio 1
	s_waitcnt lgkmcnt(0)
	v_mfma_f32_16x16x32_bf16 v[126:129], v[152:155], v[196:199], v[126:129]
	v_mfma_f32_16x16x32_bf16 v[122:125], v[172:175], v[196:199], v[122:125]
	v_mfma_f32_16x16x32_bf16 v[110:113], v[152:155], v[204:207], v[110:113]
	v_mfma_f32_16x16x32_bf16 v[106:109], v[172:175], v[204:207], v[106:109]
	v_mfma_f32_16x16x32_bf16 v[94:97], v[152:155], v[212:215], v[94:97]
	v_mfma_f32_16x16x32_bf16 v[90:93], v[172:175], v[212:215], v[90:93]
	v_mfma_f32_16x16x32_bf16 v[78:81], v[152:155], v[220:223], v[78:81]
	v_mfma_f32_16x16x32_bf16 v[74:77], v[172:175], v[220:223], v[74:77]
	v_mfma_f32_16x16x32_bf16 v[126:129], v[156:159], v[200:203], v[126:129]
	v_mfma_f32_16x16x32_bf16 v[122:125], v[176:179], v[200:203], v[122:125]
	v_mfma_f32_16x16x32_bf16 v[110:113], v[156:159], v[208:211], v[110:113]
	v_mfma_f32_16x16x32_bf16 v[106:109], v[176:179], v[208:211], v[106:109]
	v_mfma_f32_16x16x32_bf16 v[94:97], v[156:159], v[216:219], v[94:97]
	v_mfma_f32_16x16x32_bf16 v[90:93], v[176:179], v[216:219], v[90:93]
	v_mfma_f32_16x16x32_bf16 v[78:81], v[156:159], v[224:227], v[78:81]
	v_mfma_f32_16x16x32_bf16 v[74:77], v[176:179], v[224:227], v[74:77]
	s_setprio 0
	s_setprio 1
	v_mfma_f32_16x16x32_bf16 v[118:121], v[180:183], v[196:199], v[118:121]
	v_mfma_f32_16x16x32_bf16 v[114:117], v[188:191], v[196:199], v[114:117]
	v_mfma_f32_16x16x32_bf16 v[102:105], v[180:183], v[204:207], v[102:105]
	v_mfma_f32_16x16x32_bf16 v[98:101], v[188:191], v[204:207], v[98:101]
	v_mfma_f32_16x16x32_bf16 v[86:89], v[180:183], v[212:215], v[86:89]
	v_mfma_f32_16x16x32_bf16 v[82:85], v[188:191], v[212:215], v[82:85]
	v_mfma_f32_16x16x32_bf16 v[70:73], v[180:183], v[220:223], v[70:73]
	v_mfma_f32_16x16x32_bf16 v[66:69], v[188:191], v[220:223], v[66:69]
	v_mfma_f32_16x16x32_bf16 v[118:121], v[184:187], v[200:203], v[118:121]
	v_mfma_f32_16x16x32_bf16 v[114:117], v[192:195], v[200:203], v[114:117]
	v_mfma_f32_16x16x32_bf16 v[102:105], v[184:187], v[208:211], v[102:105]
	v_mfma_f32_16x16x32_bf16 v[98:101], v[192:195], v[208:211], v[98:101]
	v_mfma_f32_16x16x32_bf16 v[86:89], v[184:187], v[216:219], v[86:89]
	v_mfma_f32_16x16x32_bf16 v[82:85], v[192:195], v[216:219], v[82:85]
	v_mfma_f32_16x16x32_bf16 v[70:73], v[184:187], v[224:227], v[70:73]
	v_mfma_f32_16x16x32_bf16 v[66:69], v[192:195], v[224:227], v[66:69]
	s_setprio 0
	s_barrier
	s_add_i32 s72, s93, s78
	v_lshl_add_u64 v[228:229], s[62:63], 0, v[134:135]
	s_mov_b32 m0, s72
	ds_read_b128 v[196:199], v168 offset:16384
	ds_read_b128 v[200:203], v168 offset:17408
	ds_read_b128 v[204:207], v168 offset:18432
	ds_read_b128 v[208:211], v168 offset:19456
	ds_read_b128 v[212:215], v168 offset:20480
	ds_read_b128 v[216:219], v168 offset:21504
	ds_read_b128 v[220:223], v168 offset:22528
	ds_read_b128 v[224:227], v168 offset:23552
	global_load_lds_dwordx4 v[228:229], off
	s_add_i32 m0, s72, 0x2000
	s_add_u32 s96, s62, 0x80000
	v_lshl_add_u64 v[230:231], s[62:63], 0, v[138:139]
	s_addc_u32 s97, s63, 0
	s_add_i32 s72, s94, s78
	global_load_lds_dwordx4 v[230:231], off
	s_mov_b32 m0, s72
	v_lshl_add_u64 v[234:235], s[64:65], 0, v[136:137]
	global_load_lds_dwordx4 v134, s[96:97]
	s_add_i32 m0, s72, 0x2000
	s_nop 0
	global_load_lds_dwordx4 v138, s[96:97]
	v_lshl_add_u64 v[232:233], s[64:65], 0, v[132:133]
	s_mov_b32 m0, s79
	s_nop 0
	global_load_lds_dwordx4 v[232:233], off
	s_mov_b32 m0, s80
	s_nop 0
	global_load_lds_dwordx4 v[234:235], off
	s_waitcnt vmcnt(8)
	s_waitcnt lgkmcnt(0)
	s_barrier
	s_setprio 1
	s_waitcnt lgkmcnt(0)
	v_mfma_f32_16x16x32_bf16 v[62:65], v[152:155], v[196:199], v[62:65]
	v_mfma_f32_16x16x32_bf16 v[58:61], v[172:175], v[196:199], v[58:61]
	v_mfma_f32_16x16x32_bf16 v[46:49], v[152:155], v[204:207], v[46:49]
	v_mfma_f32_16x16x32_bf16 v[42:45], v[172:175], v[204:207], v[42:45]
	v_mfma_f32_16x16x32_bf16 v[30:33], v[152:155], v[212:215], v[30:33]
	v_mfma_f32_16x16x32_bf16 v[26:29], v[172:175], v[212:215], v[26:29]
	v_mfma_f32_16x16x32_bf16 v[14:17], v[152:155], v[220:223], v[14:17]
	v_mfma_f32_16x16x32_bf16 v[10:13], v[172:175], v[220:223], v[10:13]
	v_mfma_f32_16x16x32_bf16 v[62:65], v[156:159], v[200:203], v[62:65]
	v_mfma_f32_16x16x32_bf16 v[58:61], v[176:179], v[200:203], v[58:61]
	v_mfma_f32_16x16x32_bf16 v[46:49], v[156:159], v[208:211], v[46:49]
	v_mfma_f32_16x16x32_bf16 v[42:45], v[176:179], v[208:211], v[42:45]
	v_mfma_f32_16x16x32_bf16 v[30:33], v[156:159], v[216:219], v[30:33]
	v_mfma_f32_16x16x32_bf16 v[26:29], v[176:179], v[216:219], v[26:29]
	v_mfma_f32_16x16x32_bf16 v[14:17], v[156:159], v[224:227], v[14:17]
	v_mfma_f32_16x16x32_bf16 v[10:13], v[176:179], v[224:227], v[10:13]
	s_setprio 0
	s_setprio 1
	v_mfma_f32_16x16x32_bf16 v[54:57], v[180:183], v[196:199], v[54:57]
	v_mfma_f32_16x16x32_bf16 v[50:53], v[188:191], v[196:199], v[50:53]
	v_mfma_f32_16x16x32_bf16 v[38:41], v[180:183], v[204:207], v[38:41]
	v_mfma_f32_16x16x32_bf16 v[34:37], v[188:191], v[204:207], v[34:37]
	v_mfma_f32_16x16x32_bf16 v[22:25], v[180:183], v[212:215], v[22:25]
	v_mfma_f32_16x16x32_bf16 v[18:21], v[188:191], v[212:215], v[18:21]
	v_mfma_f32_16x16x32_bf16 v[6:9], v[180:183], v[220:223], v[6:9]
	v_mfma_f32_16x16x32_bf16 v[2:5], v[188:191], v[220:223], v[2:5]
	v_mfma_f32_16x16x32_bf16 v[54:57], v[184:187], v[200:203], v[54:57]
	v_mfma_f32_16x16x32_bf16 v[50:53], v[192:195], v[200:203], v[50:53]
	v_mfma_f32_16x16x32_bf16 v[38:41], v[184:187], v[208:211], v[38:41]
	v_mfma_f32_16x16x32_bf16 v[34:37], v[192:195], v[208:211], v[34:37]
	v_mfma_f32_16x16x32_bf16 v[22:25], v[184:187], v[216:219], v[22:25]
	v_mfma_f32_16x16x32_bf16 v[18:21], v[192:195], v[216:219], v[18:21]
	v_mfma_f32_16x16x32_bf16 v[6:9], v[184:187], v[224:227], v[6:9]
	v_mfma_f32_16x16x32_bf16 v[2:5], v[192:195], v[224:227], v[2:5]
	s_setprio 0
	s_barrier
	s_add_i32 s72, 0, 0x18000
	v_add_u32_e32 v171, s72, v160
	s_add_i32 s73, 0, 0x1c000
	ds_read_b128 v[152:155], v171
	ds_read_b128 v[156:159], v171 offset:1024
	ds_read_b128 v[172:175], v171 offset:2048
	ds_read_b128 v[176:179], v171 offset:3072
	v_add_u32_e32 v171, s73, v160
	ds_read_b128 v[180:183], v171
	ds_read_b128 v[184:187], v171 offset:1024
	ds_read_b128 v[188:191], v171 offset:2048
	ds_read_b128 v[192:195], v171 offset:3072
	s_add_u32 s64, s64, 0x80000
	s_addc_u32 s65, s65, 0
	s_mov_b32 m0, s81
	ds_read_b128 v[196:199], v168 offset:32768
	ds_read_b128 v[200:203], v168 offset:33792
	ds_read_b128 v[204:207], v168 offset:34816
	ds_read_b128 v[208:211], v168 offset:35840
	ds_read_b128 v[212:215], v168 offset:36864
	ds_read_b128 v[216:219], v168 offset:37888
	ds_read_b128 v[220:223], v168 offset:38912
	ds_read_b128 v[224:227], v168 offset:39936
	global_load_lds_dwordx4 v132, s[64:65]
	s_mov_b32 m0, s82
	s_nop 0
	global_load_lds_dwordx4 v136, s[64:65]
	s_waitcnt vmcnt(8)
	s_waitcnt lgkmcnt(0)
	s_barrier
	s_setprio 1
	s_waitcnt lgkmcnt(0)
	v_mfma_f32_16x16x32_bf16 v[126:129], v[152:155], v[196:199], v[126:129]
	v_mfma_f32_16x16x32_bf16 v[122:125], v[172:175], v[196:199], v[122:125]
	v_mfma_f32_16x16x32_bf16 v[110:113], v[152:155], v[204:207], v[110:113]
	v_mfma_f32_16x16x32_bf16 v[106:109], v[172:175], v[204:207], v[106:109]
	v_mfma_f32_16x16x32_bf16 v[94:97], v[152:155], v[212:215], v[94:97]
	v_mfma_f32_16x16x32_bf16 v[90:93], v[172:175], v[212:215], v[90:93]
	v_mfma_f32_16x16x32_bf16 v[78:81], v[152:155], v[220:223], v[78:81]
	v_mfma_f32_16x16x32_bf16 v[74:77], v[172:175], v[220:223], v[74:77]
	v_mfma_f32_16x16x32_bf16 v[126:129], v[156:159], v[200:203], v[126:129]
	v_mfma_f32_16x16x32_bf16 v[122:125], v[176:179], v[200:203], v[122:125]
	v_mfma_f32_16x16x32_bf16 v[110:113], v[156:159], v[208:211], v[110:113]
	v_mfma_f32_16x16x32_bf16 v[106:109], v[176:179], v[208:211], v[106:109]
	v_mfma_f32_16x16x32_bf16 v[94:97], v[156:159], v[216:219], v[94:97]
	v_mfma_f32_16x16x32_bf16 v[90:93], v[176:179], v[216:219], v[90:93]
	v_mfma_f32_16x16x32_bf16 v[78:81], v[156:159], v[224:227], v[78:81]
	v_mfma_f32_16x16x32_bf16 v[74:77], v[176:179], v[224:227], v[74:77]
	s_setprio 0
	s_setprio 1
	v_mfma_f32_16x16x32_bf16 v[118:121], v[180:183], v[196:199], v[118:121]
	v_mfma_f32_16x16x32_bf16 v[114:117], v[188:191], v[196:199], v[114:117]
	v_mfma_f32_16x16x32_bf16 v[102:105], v[180:183], v[204:207], v[102:105]
	v_mfma_f32_16x16x32_bf16 v[98:101], v[188:191], v[204:207], v[98:101]
	v_mfma_f32_16x16x32_bf16 v[86:89], v[180:183], v[212:215], v[86:89]
	v_mfma_f32_16x16x32_bf16 v[82:85], v[188:191], v[212:215], v[82:85]
	v_mfma_f32_16x16x32_bf16 v[70:73], v[180:183], v[220:223], v[70:73]
	v_mfma_f32_16x16x32_bf16 v[66:69], v[188:191], v[220:223], v[66:69]
	v_mfma_f32_16x16x32_bf16 v[118:121], v[184:187], v[200:203], v[118:121]
	v_mfma_f32_16x16x32_bf16 v[114:117], v[192:195], v[200:203], v[114:117]
	v_mfma_f32_16x16x32_bf16 v[102:105], v[184:187], v[208:211], v[102:105]
	v_mfma_f32_16x16x32_bf16 v[98:101], v[192:195], v[208:211], v[98:101]
	v_mfma_f32_16x16x32_bf16 v[86:89], v[184:187], v[216:219], v[86:89]
	v_mfma_f32_16x16x32_bf16 v[82:85], v[192:195], v[216:219], v[82:85]
	v_mfma_f32_16x16x32_bf16 v[70:73], v[184:187], v[224:227], v[70:73]
	v_mfma_f32_16x16x32_bf16 v[66:69], v[192:195], v[224:227], v[66:69]
	s_setprio 0
	s_barrier
	s_add_i32 s64, s72, s78
	v_lshl_add_u64 v[228:229], v[228:229], 0, s[20:21]
	s_mov_b32 m0, s64
	ds_read_b128 v[196:199], v168 offset:49152
	ds_read_b128 v[200:203], v168 offset:50176
	ds_read_b128 v[204:207], v168 offset:51200
	ds_read_b128 v[208:211], v168 offset:52224
	ds_read_b128 v[212:215], v168 offset:53248
	ds_read_b128 v[216:219], v168 offset:54272
	ds_read_b128 v[220:223], v168 offset:55296
	ds_read_b128 v[224:227], v168 offset:56320
	global_load_lds_dwordx4 v[228:229], off
	s_add_i32 m0, s64, 0x2000
	s_add_u32 s62, s62, 0x80080
	v_lshl_add_u64 v[228:229], v[230:231], 0, s[20:21]
	s_addc_u32 s63, s63, 0
	s_add_i32 s64, s73, s78
	global_load_lds_dwordx4 v[228:229], off
	s_mov_b32 m0, s64
	s_nop 0
	global_load_lds_dwordx4 v134, s[62:63]
	s_add_i32 m0, s64, 0x2000
	s_nop 0
	global_load_lds_dwordx4 v138, s[62:63]
	v_lshl_add_u64 v[228:229], v[232:233], 0, s[20:21]
	s_mov_b32 m0, s90
	s_nop 0
	global_load_lds_dwordx4 v[228:229], off
	v_lshl_add_u64 v[228:229], v[234:235], 0, s[20:21]
	s_mov_b32 m0, s91
	s_nop 0
	global_load_lds_dwordx4 v[228:229], off
	s_waitcnt vmcnt(8)
	s_waitcnt lgkmcnt(0)
	s_barrier
	s_setprio 1
	s_waitcnt lgkmcnt(0)
	v_mfma_f32_16x16x32_bf16 v[62:65], v[152:155], v[196:199], v[62:65]
	v_mfma_f32_16x16x32_bf16 v[58:61], v[172:175], v[196:199], v[58:61]
	v_mfma_f32_16x16x32_bf16 v[46:49], v[152:155], v[204:207], v[46:49]
	v_mfma_f32_16x16x32_bf16 v[42:45], v[172:175], v[204:207], v[42:45]
	v_mfma_f32_16x16x32_bf16 v[30:33], v[152:155], v[212:215], v[30:33]
	v_mfma_f32_16x16x32_bf16 v[26:29], v[172:175], v[212:215], v[26:29]
	v_mfma_f32_16x16x32_bf16 v[14:17], v[152:155], v[220:223], v[14:17]
	v_mfma_f32_16x16x32_bf16 v[10:13], v[172:175], v[220:223], v[10:13]
	v_mfma_f32_16x16x32_bf16 v[62:65], v[156:159], v[200:203], v[62:65]
	v_mfma_f32_16x16x32_bf16 v[58:61], v[176:179], v[200:203], v[58:61]
	v_mfma_f32_16x16x32_bf16 v[46:49], v[156:159], v[208:211], v[46:49]
	v_mfma_f32_16x16x32_bf16 v[42:45], v[176:179], v[208:211], v[42:45]
	v_mfma_f32_16x16x32_bf16 v[30:33], v[156:159], v[216:219], v[30:33]
	v_mfma_f32_16x16x32_bf16 v[26:29], v[176:179], v[216:219], v[26:29]
	v_mfma_f32_16x16x32_bf16 v[14:17], v[156:159], v[224:227], v[14:17]
	v_mfma_f32_16x16x32_bf16 v[10:13], v[176:179], v[224:227], v[10:13]
	s_setprio 0
	s_setprio 1
	v_mfma_f32_16x16x32_bf16 v[54:57], v[180:183], v[196:199], v[54:57]
	v_mfma_f32_16x16x32_bf16 v[50:53], v[188:191], v[196:199], v[50:53]
	v_mfma_f32_16x16x32_bf16 v[38:41], v[180:183], v[204:207], v[38:41]
	v_mfma_f32_16x16x32_bf16 v[34:37], v[188:191], v[204:207], v[34:37]
	v_mfma_f32_16x16x32_bf16 v[22:25], v[180:183], v[212:215], v[22:25]
	v_mfma_f32_16x16x32_bf16 v[18:21], v[188:191], v[212:215], v[18:21]
	v_mfma_f32_16x16x32_bf16 v[6:9], v[180:183], v[220:223], v[6:9]
	v_mfma_f32_16x16x32_bf16 v[2:5], v[188:191], v[220:223], v[2:5]
	v_mfma_f32_16x16x32_bf16 v[54:57], v[184:187], v[200:203], v[54:57]
	v_mfma_f32_16x16x32_bf16 v[50:53], v[192:195], v[200:203], v[50:53]
	v_mfma_f32_16x16x32_bf16 v[38:41], v[184:187], v[208:211], v[38:41]
	v_mfma_f32_16x16x32_bf16 v[34:37], v[192:195], v[208:211], v[34:37]
	v_mfma_f32_16x16x32_bf16 v[22:25], v[184:187], v[216:219], v[22:25]
	v_mfma_f32_16x16x32_bf16 v[18:21], v[192:195], v[216:219], v[18:21]
	v_mfma_f32_16x16x32_bf16 v[6:9], v[184:187], v[224:227], v[6:9]
	v_mfma_f32_16x16x32_bf16 v[2:5], v[192:195], v[224:227], v[2:5]
	s_setprio 0
	s_barrier
	s_add_i32 s74, s74, 2
	s_add_u32 s8, s8, 0x100
	s_addc_u32 s9, s9, 0
	s_add_u32 s49, s49, 0x100
	s_addc_u32 s61, s61, 0
	s_cmp_gt_u32 s74, 29
	s_cbranch_scc0 .LBB0_266
	s_and_b64 vcc, exec, s[22:23]
	s_cbranch_vccz .LBB0_269
	s_barrier

.LBB0_447:
	ds_read_b128 v[150:153], v167
	ds_read_b128 v[154:157], v167 offset:1024
	ds_read_b128 v[174:177], v167 offset:2048
	ds_read_b128 v[178:181], v167 offset:3072
	ds_read_b128 v[182:185], v168
	ds_read_b128 v[186:189], v168 offset:1024
	ds_read_b128 v[190:193], v168 offset:2048
	ds_read_b128 v[194:197], v168 offset:3072
	s_add_u32 s44, s6, 0xffe00080
	s_addc_u32 s45, s7, -1
	s_cmp_eq_u32 s74, 4
	s_cselect_b32 s49, s1, s45
	s_cselect_b32 s48, s5, s44
	s_cselect_b32 s45, s12, s39
	s_cselect_b32 s44, s13, s25
	s_add_i32 m0, s62, 0xc000
	ds_read_b128 v[198:201], v169
	ds_read_b128 v[202:205], v169 offset:1024
	ds_read_b128 v[206:209], v169 offset:2048
	ds_read_b128 v[210:213], v169 offset:3072
	ds_read_b128 v[214:217], v169 offset:4096
	ds_read_b128 v[218:221], v169 offset:5120
	ds_read_b128 v[222:225], v169 offset:6144
	ds_read_b128 v[226:229], v169 offset:7168
	global_load_lds_dwordx4 v140, s[6:7]
	s_add_i32 m0, s62, 0xe000
	s_nop 0
	global_load_lds_dwordx4 v142, s[6:7]
	s_waitcnt vmcnt(8)
	s_waitcnt lgkmcnt(0)
	s_barrier
	s_setprio 1
	s_waitcnt lgkmcnt(0)
	v_mfma_f32_16x16x32_bf16 v[126:129], v[150:153], v[198:201], v[126:129]
	v_mfma_f32_16x16x32_bf16 v[122:125], v[174:177], v[198:201], v[122:125]
	v_mfma_f32_16x16x32_bf16 v[110:113], v[150:153], v[206:209], v[110:113]
	v_mfma_f32_16x16x32_bf16 v[106:109], v[174:177], v[206:209], v[106:109]
	v_mfma_f32_16x16x32_bf16 v[94:97], v[150:153], v[214:217], v[94:97]
	v_mfma_f32_16x16x32_bf16 v[90:93], v[174:177], v[214:217], v[90:93]
	v_mfma_f32_16x16x32_bf16 v[78:81], v[150:153], v[222:225], v[78:81]
	v_mfma_f32_16x16x32_bf16 v[74:77], v[174:177], v[222:225], v[74:77]
	v_mfma_f32_16x16x32_bf16 v[126:129], v[154:157], v[202:205], v[126:129]
	v_mfma_f32_16x16x32_bf16 v[122:125], v[178:181], v[202:205], v[122:125]
	v_mfma_f32_16x16x32_bf16 v[110:113], v[154:157], v[210:213], v[110:113]
	v_mfma_f32_16x16x32_bf16 v[106:109], v[178:181], v[210:213], v[106:109]
	v_mfma_f32_16x16x32_bf16 v[94:97], v[154:157], v[218:221], v[94:97]
	v_mfma_f32_16x16x32_bf16 v[90:93], v[178:181], v[218:221], v[90:93]
	v_mfma_f32_16x16x32_bf16 v[78:81], v[154:157], v[226:229], v[78:81]
	v_mfma_f32_16x16x32_bf16 v[74:77], v[178:181], v[226:229], v[74:77]
	s_setprio 0
	s_setprio 1
	v_mfma_f32_16x16x32_bf16 v[118:121], v[182:185], v[198:201], v[118:121]
	v_mfma_f32_16x16x32_bf16 v[114:117], v[190:193], v[198:201], v[114:117]
	v_mfma_f32_16x16x32_bf16 v[102:105], v[182:185], v[206:209], v[102:105]
	v_mfma_f32_16x16x32_bf16 v[98:101], v[190:193], v[206:209], v[98:101]
	v_mfma_f32_16x16x32_bf16 v[86:89], v[182:185], v[214:217], v[86:89]
	v_mfma_f32_16x16x32_bf16 v[82:85], v[190:193], v[214:217], v[82:85]
	v_mfma_f32_16x16x32_bf16 v[70:73], v[182:185], v[222:225], v[70:73]
	v_mfma_f32_16x16x32_bf16 v[66:69], v[190:193], v[222:225], v[66:69]
	v_mfma_f32_16x16x32_bf16 v[118:121], v[186:189], v[202:205], v[118:121]
	v_mfma_f32_16x16x32_bf16 v[114:117], v[194:197], v[202:205], v[114:117]
	v_mfma_f32_16x16x32_bf16 v[102:105], v[186:189], v[210:213], v[102:105]
	v_mfma_f32_16x16x32_bf16 v[98:101], v[194:197], v[210:213], v[98:101]
	v_mfma_f32_16x16x32_bf16 v[86:89], v[186:189], v[218:221], v[86:89]
	v_mfma_f32_16x16x32_bf16 v[82:85], v[194:197], v[218:221], v[82:85]
	v_mfma_f32_16x16x32_bf16 v[70:73], v[186:189], v[226:229], v[70:73]
	v_mfma_f32_16x16x32_bf16 v[66:69], v[194:197], v[226:229], v[66:69]
	s_setprio 0
	s_barrier
	s_add_i32 s72, s79, s61
	v_lshl_add_u64 v[158:159], s[44:45], 0, v[132:133]
	s_mov_b32 m0, s72
	ds_read_b128 v[198:201], v169 offset:16384
	ds_read_b128 v[202:205], v169 offset:17408
	ds_read_b128 v[206:209], v169 offset:18432
	ds_read_b128 v[210:213], v169 offset:19456
	ds_read_b128 v[214:217], v169 offset:20480
	ds_read_b128 v[218:221], v169 offset:21504
	ds_read_b128 v[222:225], v169 offset:22528
	ds_read_b128 v[226:229], v169 offset:23552
	global_load_lds_dwordx4 v[158:159], off
	s_add_i32 m0, s72, 0x2000
	s_add_u32 s84, s44, 0x20000
	v_lshl_add_u64 v[230:231], s[44:45], 0, v[136:137]
	s_addc_u32 s85, s45, 0
	s_add_i32 s72, s80, s61
	global_load_lds_dwordx4 v[230:231], off
	s_mov_b32 m0, s72
	v_lshl_add_u64 v[234:235], s[48:49], 0, v[134:135]
	global_load_lds_dwordx4 v132, s[84:85]
	s_add_i32 m0, s72, 0x2000
	s_nop 0
	global_load_lds_dwordx4 v136, s[84:85]
	v_lshl_add_u64 v[232:233], s[48:49], 0, v[130:131]
	s_mov_b32 m0, s62
	s_nop 0
	global_load_lds_dwordx4 v[232:233], off
	s_mov_b32 m0, s63
	s_nop 0
	global_load_lds_dwordx4 v[234:235], off
	s_waitcnt vmcnt(8)
	s_waitcnt lgkmcnt(0)
	s_barrier
	s_setprio 1
	s_waitcnt lgkmcnt(0)
	v_mfma_f32_16x16x32_bf16 v[62:65], v[150:153], v[198:201], v[62:65]
	v_mfma_f32_16x16x32_bf16 v[58:61], v[174:177], v[198:201], v[58:61]
	v_mfma_f32_16x16x32_bf16 v[46:49], v[150:153], v[206:209], v[46:49]
	v_mfma_f32_16x16x32_bf16 v[42:45], v[174:177], v[206:209], v[42:45]
	v_mfma_f32_16x16x32_bf16 v[30:33], v[150:153], v[214:217], v[30:33]
	v_mfma_f32_16x16x32_bf16 v[26:29], v[174:177], v[214:217], v[26:29]
	v_mfma_f32_16x16x32_bf16 v[14:17], v[150:153], v[222:225], v[14:17]
	v_mfma_f32_16x16x32_bf16 v[10:13], v[174:177], v[222:225], v[10:13]
	v_mfma_f32_16x16x32_bf16 v[62:65], v[154:157], v[202:205], v[62:65]
	v_mfma_f32_16x16x32_bf16 v[58:61], v[178:181], v[202:205], v[58:61]
	v_mfma_f32_16x16x32_bf16 v[46:49], v[154:157], v[210:213], v[46:49]
	v_mfma_f32_16x16x32_bf16 v[42:45], v[178:181], v[210:213], v[42:45]
	v_mfma_f32_16x16x32_bf16 v[30:33], v[154:157], v[218:221], v[30:33]
	v_mfma_f32_16x16x32_bf16 v[26:29], v[178:181], v[218:221], v[26:29]
	v_mfma_f32_16x16x32_bf16 v[14:17], v[154:157], v[226:229], v[14:17]
	v_mfma_f32_16x16x32_bf16 v[10:13], v[178:181], v[226:229], v[10:13]
	s_setprio 0
	s_setprio 1
	v_mfma_f32_16x16x32_bf16 v[54:57], v[182:185], v[198:201], v[54:57]
	v_mfma_f32_16x16x32_bf16 v[50:53], v[190:193], v[198:201], v[50:53]
	v_mfma_f32_16x16x32_bf16 v[38:41], v[182:185], v[206:209], v[38:41]
	v_mfma_f32_16x16x32_bf16 v[34:37], v[190:193], v[206:209], v[34:37]
	v_mfma_f32_16x16x32_bf16 v[22:25], v[182:185], v[214:217], v[22:25]
	v_mfma_f32_16x16x32_bf16 v[18:21], v[190:193], v[214:217], v[18:21]
	v_mfma_f32_16x16x32_bf16 v[6:9], v[182:185], v[222:225], v[6:9]
	v_mfma_f32_16x16x32_bf16 v[2:5], v[190:193], v[222:225], v[2:5]
	v_mfma_f32_16x16x32_bf16 v[54:57], v[186:189], v[202:205], v[54:57]
	v_mfma_f32_16x16x32_bf16 v[50:53], v[194:197], v[202:205], v[50:53]
	v_mfma_f32_16x16x32_bf16 v[38:41], v[186:189], v[210:213], v[38:41]
	v_mfma_f32_16x16x32_bf16 v[34:37], v[194:197], v[210:213], v[34:37]
	v_mfma_f32_16x16x32_bf16 v[22:25], v[186:189], v[218:221], v[22:25]
	v_mfma_f32_16x16x32_bf16 v[18:21], v[194:197], v[218:221], v[18:21]
	v_mfma_f32_16x16x32_bf16 v[6:9], v[186:189], v[226:229], v[6:9]
	v_mfma_f32_16x16x32_bf16 v[2:5], v[194:197], v[226:229], v[2:5]
	s_setprio 0
	s_barrier
	s_add_i32 s72, 0, 0x18000
	v_add_u32_e32 v173, s72, v161
	s_add_i32 s73, 0, 0x1c000
	ds_read_b128 v[150:153], v173
	ds_read_b128 v[154:157], v173 offset:1024
	ds_read_b128 v[174:177], v173 offset:2048
	ds_read_b128 v[178:181], v173 offset:3072
	v_add_u32_e32 v173, s73, v161
	ds_read_b128 v[182:185], v173
	ds_read_b128 v[186:189], v173 offset:1024
	ds_read_b128 v[190:193], v173 offset:2048
	ds_read_b128 v[194:197], v173 offset:3072
	s_add_u32 s48, s48, 0x200000
	s_addc_u32 s49, s49, 0
	s_mov_b32 m0, s64
	ds_read_b128 v[198:201], v169 offset:32768
	ds_read_b128 v[202:205], v169 offset:33792
	ds_read_b128 v[206:209], v169 offset:34816
	ds_read_b128 v[210:213], v169 offset:35840
	ds_read_b128 v[214:217], v169 offset:36864
	ds_read_b128 v[218:221], v169 offset:37888
	ds_read_b128 v[222:225], v169 offset:38912
	ds_read_b128 v[226:229], v169 offset:39936
	global_load_lds_dwordx4 v130, s[48:49]
	s_mov_b32 m0, s65
	s_nop 0
	global_load_lds_dwordx4 v134, s[48:49]
	s_waitcnt vmcnt(8)
	s_waitcnt lgkmcnt(0)
	s_barrier
	s_setprio 1
	s_waitcnt lgkmcnt(0)
	v_mfma_f32_16x16x32_bf16 v[126:129], v[150:153], v[198:201], v[126:129]
	v_mfma_f32_16x16x32_bf16 v[122:125], v[174:177], v[198:201], v[122:125]
	v_mfma_f32_16x16x32_bf16 v[110:113], v[150:153], v[206:209], v[110:113]
	v_mfma_f32_16x16x32_bf16 v[106:109], v[174:177], v[206:209], v[106:109]
	v_mfma_f32_16x16x32_bf16 v[94:97], v[150:153], v[214:217], v[94:97]
	v_mfma_f32_16x16x32_bf16 v[90:93], v[174:177], v[214:217], v[90:93]
	v_mfma_f32_16x16x32_bf16 v[78:81], v[150:153], v[222:225], v[78:81]
	v_mfma_f32_16x16x32_bf16 v[74:77], v[174:177], v[222:225], v[74:77]
	v_mfma_f32_16x16x32_bf16 v[126:129], v[154:157], v[202:205], v[126:129]
	v_mfma_f32_16x16x32_bf16 v[122:125], v[178:181], v[202:205], v[122:125]
	v_mfma_f32_16x16x32_bf16 v[110:113], v[154:157], v[210:213], v[110:113]
	v_mfma_f32_16x16x32_bf16 v[106:109], v[178:181], v[210:213], v[106:109]
	v_mfma_f32_16x16x32_bf16 v[94:97], v[154:157], v[218:221], v[94:97]
	v_mfma_f32_16x16x32_bf16 v[90:93], v[178:181], v[218:221], v[90:93]
	v_mfma_f32_16x16x32_bf16 v[78:81], v[154:157], v[226:229], v[78:81]
	v_mfma_f32_16x16x32_bf16 v[74:77], v[178:181], v[226:229], v[74:77]
	s_setprio 0
	s_setprio 1
	v_mfma_f32_16x16x32_bf16 v[118:121], v[182:185], v[198:201], v[118:121]
	v_mfma_f32_16x16x32_bf16 v[114:117], v[190:193], v[198:201], v[114:117]
	v_mfma_f32_16x16x32_bf16 v[102:105], v[182:185], v[206:209], v[102:105]
	v_mfma_f32_16x16x32_bf16 v[98:101], v[190:193], v[206:209], v[98:101]
	v_mfma_f32_16x16x32_bf16 v[86:89], v[182:185], v[214:217], v[86:89]
	v_mfma_f32_16x16x32_bf16 v[82:85], v[190:193], v[214:217], v[82:85]
	v_mfma_f32_16x16x32_bf16 v[70:73], v[182:185], v[222:225], v[70:73]
	v_mfma_f32_16x16x32_bf16 v[66:69], v[190:193], v[222:225], v[66:69]
	v_mfma_f32_16x16x32_bf16 v[118:121], v[186:189], v[202:205], v[118:121]
	v_mfma_f32_16x16x32_bf16 v[114:117], v[194:197], v[202:205], v[114:117]
	v_mfma_f32_16x16x32_bf16 v[102:105], v[186:189], v[210:213], v[102:105]
	v_mfma_f32_16x16x32_bf16 v[98:101], v[194:197], v[210:213], v[98:101]
	v_mfma_f32_16x16x32_bf16 v[86:89], v[186:189], v[218:221], v[86:89]
	v_mfma_f32_16x16x32_bf16 v[82:85], v[194:197], v[218:221], v[82:85]
	v_mfma_f32_16x16x32_bf16 v[70:73], v[186:189], v[226:229], v[70:73]
	v_mfma_f32_16x16x32_bf16 v[66:69], v[194:197], v[226:229], v[66:69]
	s_setprio 0
	s_barrier
	s_add_i32 s48, s72, s61
	v_lshl_add_u64 v[158:159], v[158:159], 0, s[20:21]
	s_mov_b32 m0, s48
	ds_read_b128 v[198:201], v169 offset:49152
	ds_read_b128 v[202:205], v169 offset:50176
	ds_read_b128 v[206:209], v169 offset:51200
	ds_read_b128 v[210:213], v169 offset:52224
	ds_read_b128 v[214:217], v169 offset:53248
	ds_read_b128 v[218:221], v169 offset:54272
	ds_read_b128 v[222:225], v169 offset:55296
	ds_read_b128 v[226:229], v169 offset:56320
	global_load_lds_dwordx4 v[158:159], off
	s_add_i32 m0, s48, 0x2000
	s_add_u32 s44, s44, 0x20080
	v_lshl_add_u64 v[158:159], v[230:231], 0, s[20:21]
	s_addc_u32 s45, s45, 0
	s_add_i32 s48, s73, s61
	global_load_lds_dwordx4 v[158:159], off
	s_mov_b32 m0, s48
	s_nop 0
	global_load_lds_dwordx4 v132, s[44:45]
	s_add_i32 m0, s48, 0x2000
	s_nop 0
	global_load_lds_dwordx4 v136, s[44:45]
	v_lshl_add_u64 v[158:159], v[232:233], 0, s[20:21]
	s_mov_b32 m0, s77
	s_nop 0
	global_load_lds_dwordx4 v[158:159], off
	v_lshl_add_u64 v[158:159], v[234:235], 0, s[20:21]
	s_mov_b32 m0, s78
	s_nop 0
	global_load_lds_dwordx4 v[158:159], off
	s_waitcnt vmcnt(8)
	s_waitcnt lgkmcnt(0)
	s_barrier
	s_setprio 1
	s_waitcnt lgkmcnt(0)
	v_mfma_f32_16x16x32_bf16 v[62:65], v[150:153], v[198:201], v[62:65]
	v_mfma_f32_16x16x32_bf16 v[58:61], v[174:177], v[198:201], v[58:61]
	v_mfma_f32_16x16x32_bf16 v[46:49], v[150:153], v[206:209], v[46:49]
	v_mfma_f32_16x16x32_bf16 v[42:45], v[174:177], v[206:209], v[42:45]
	v_mfma_f32_16x16x32_bf16 v[30:33], v[150:153], v[214:217], v[30:33]
	v_mfma_f32_16x16x32_bf16 v[26:29], v[174:177], v[214:217], v[26:29]
	v_mfma_f32_16x16x32_bf16 v[14:17], v[150:153], v[222:225], v[14:17]
	v_mfma_f32_16x16x32_bf16 v[10:13], v[174:177], v[222:225], v[10:13]
	v_mfma_f32_16x16x32_bf16 v[62:65], v[154:157], v[202:205], v[62:65]
	v_mfma_f32_16x16x32_bf16 v[58:61], v[178:181], v[202:205], v[58:61]
	v_mfma_f32_16x16x32_bf16 v[46:49], v[154:157], v[210:213], v[46:49]
	v_mfma_f32_16x16x32_bf16 v[42:45], v[178:181], v[210:213], v[42:45]
	v_mfma_f32_16x16x32_bf16 v[30:33], v[154:157], v[218:221], v[30:33]
	v_mfma_f32_16x16x32_bf16 v[26:29], v[178:181], v[218:221], v[26:29]
	v_mfma_f32_16x16x32_bf16 v[14:17], v[154:157], v[226:229], v[14:17]
	v_mfma_f32_16x16x32_bf16 v[10:13], v[178:181], v[226:229], v[10:13]
	s_setprio 0
	s_setprio 1
	v_mfma_f32_16x16x32_bf16 v[54:57], v[182:185], v[198:201], v[54:57]
	v_mfma_f32_16x16x32_bf16 v[50:53], v[190:193], v[198:201], v[50:53]
	v_mfma_f32_16x16x32_bf16 v[38:41], v[182:185], v[206:209], v[38:41]
	v_mfma_f32_16x16x32_bf16 v[34:37], v[190:193], v[206:209], v[34:37]
	v_mfma_f32_16x16x32_bf16 v[22:25], v[182:185], v[214:217], v[22:25]
	v_mfma_f32_16x16x32_bf16 v[18:21], v[190:193], v[214:217], v[18:21]
	v_mfma_f32_16x16x32_bf16 v[6:9], v[182:185], v[222:225], v[6:9]
	v_mfma_f32_16x16x32_bf16 v[2:5], v[190:193], v[222:225], v[2:5]
	v_mfma_f32_16x16x32_bf16 v[54:57], v[186:189], v[202:205], v[54:57]
	v_mfma_f32_16x16x32_bf16 v[50:53], v[194:197], v[202:205], v[50:53]
	v_mfma_f32_16x16x32_bf16 v[38:41], v[186:189], v[210:213], v[38:41]
	v_mfma_f32_16x16x32_bf16 v[34:37], v[194:197], v[210:213], v[34:37]
	v_mfma_f32_16x16x32_bf16 v[22:25], v[186:189], v[218:221], v[22:25]
	v_mfma_f32_16x16x32_bf16 v[18:21], v[194:197], v[218:221], v[18:21]
	v_mfma_f32_16x16x32_bf16 v[6:9], v[186:189], v[226:229], v[6:9]
	v_mfma_f32_16x16x32_bf16 v[2:5], v[194:197], v[226:229], v[2:5]
	s_setprio 0
	s_barrier
	s_add_i32 s74, s74, 2
	s_add_u32 s6, s6, 0x100
	s_addc_u32 s7, s7, 0
	s_add_u32 s25, s25, 0x100
	s_addc_u32 s39, s39, 0
	s_cmp_gt_u32 s74, 5
	s_cbranch_scc0 .LBB0_447
	s_and_b64 vcc, exec, s[22:23]
	s_cbranch_vccz .LBB0_450
	s_barrier

.LBB0_783:
	ds_read_b128 v[130:133], v164
	ds_read_b128 v[134:137], v164 offset:1024
	ds_read_b128 v[156:159], v164 offset:2048
	ds_read_b128 v[168:171], v164 offset:3072
	ds_read_b128 v[172:175], v165
	ds_read_b128 v[178:181], v165 offset:1024
	ds_read_b128 v[182:185], v165 offset:2048
	ds_read_b128 v[186:189], v165 offset:3072
	s_add_u32 s48, s44, 0xfffc0080
	s_addc_u32 s49, s45, -1
	s_cmp_eq_u32 s79, 12
	s_cselect_b32 s53, s13, s49
	s_cselect_b32 s52, s25, s48
	s_cselect_b32 s49, s23, s78
	s_cselect_b32 s48, s74, s75
	s_add_i32 m0, s43, 0xc000
	ds_read_b128 v[190:193], v166
	ds_read_b128 v[194:197], v166 offset:1024
	ds_read_b128 v[198:201], v166 offset:2048
	ds_read_b128 v[202:205], v166 offset:3072
	ds_read_b128 v[206:209], v166 offset:4096
	ds_read_b128 v[210:213], v166 offset:5120
	ds_read_b128 v[214:217], v166 offset:6144
	ds_read_b128 v[218:221], v166 offset:7168
	global_load_lds_dwordx4 v148, s[44:45]
	s_add_i32 m0, s43, 0xe000
	s_nop 0
	global_load_lds_dwordx4 v150, s[44:45]
	s_waitcnt vmcnt(8)
	s_waitcnt lgkmcnt(0)
	s_barrier
	s_setprio 1
	s_waitcnt lgkmcnt(0)
	v_mfma_f32_16x16x32_bf16 v[126:129], v[130:133], v[190:193], v[126:129]
	v_mfma_f32_16x16x32_bf16 v[122:125], v[156:159], v[190:193], v[122:125]
	v_mfma_f32_16x16x32_bf16 v[110:113], v[130:133], v[198:201], v[110:113]
	v_mfma_f32_16x16x32_bf16 v[106:109], v[156:159], v[198:201], v[106:109]
	v_mfma_f32_16x16x32_bf16 v[94:97], v[130:133], v[206:209], v[94:97]
	v_mfma_f32_16x16x32_bf16 v[90:93], v[156:159], v[206:209], v[90:93]
	v_mfma_f32_16x16x32_bf16 v[78:81], v[130:133], v[214:217], v[78:81]
	v_mfma_f32_16x16x32_bf16 v[74:77], v[156:159], v[214:217], v[74:77]
	v_mfma_f32_16x16x32_bf16 v[126:129], v[134:137], v[194:197], v[126:129]
	v_mfma_f32_16x16x32_bf16 v[122:125], v[168:171], v[194:197], v[122:125]
	v_mfma_f32_16x16x32_bf16 v[110:113], v[134:137], v[202:205], v[110:113]
	v_mfma_f32_16x16x32_bf16 v[106:109], v[168:171], v[202:205], v[106:109]
	v_mfma_f32_16x16x32_bf16 v[94:97], v[134:137], v[210:213], v[94:97]
	v_mfma_f32_16x16x32_bf16 v[90:93], v[168:171], v[210:213], v[90:93]
	v_mfma_f32_16x16x32_bf16 v[78:81], v[134:137], v[218:221], v[78:81]
	v_mfma_f32_16x16x32_bf16 v[74:77], v[168:171], v[218:221], v[74:77]
	s_setprio 0
	s_setprio 1
	v_mfma_f32_16x16x32_bf16 v[118:121], v[172:175], v[190:193], v[118:121]
	v_mfma_f32_16x16x32_bf16 v[114:117], v[182:185], v[190:193], v[114:117]
	v_mfma_f32_16x16x32_bf16 v[102:105], v[172:175], v[198:201], v[102:105]
	v_mfma_f32_16x16x32_bf16 v[98:101], v[182:185], v[198:201], v[98:101]
	v_mfma_f32_16x16x32_bf16 v[86:89], v[172:175], v[206:209], v[86:89]
	v_mfma_f32_16x16x32_bf16 v[82:85], v[182:185], v[206:209], v[82:85]
	v_mfma_f32_16x16x32_bf16 v[70:73], v[172:175], v[214:217], v[70:73]
	v_mfma_f32_16x16x32_bf16 v[66:69], v[182:185], v[214:217], v[66:69]
	v_mfma_f32_16x16x32_bf16 v[118:121], v[178:181], v[194:197], v[118:121]
	v_mfma_f32_16x16x32_bf16 v[114:117], v[186:189], v[194:197], v[114:117]
	v_mfma_f32_16x16x32_bf16 v[102:105], v[178:181], v[202:205], v[102:105]
	v_mfma_f32_16x16x32_bf16 v[98:101], v[186:189], v[202:205], v[98:101]
	v_mfma_f32_16x16x32_bf16 v[86:89], v[178:181], v[210:213], v[86:89]
	v_mfma_f32_16x16x32_bf16 v[82:85], v[186:189], v[210:213], v[82:85]
	v_mfma_f32_16x16x32_bf16 v[70:73], v[178:181], v[218:221], v[70:73]
	v_mfma_f32_16x16x32_bf16 v[66:69], v[186:189], v[218:221], v[66:69]
	s_setprio 0
	s_barrier
	s_add_i32 s72, s76, s62
	v_lshl_add_u64 v[160:161], s[48:49], 0, v[142:143]
	s_mov_b32 m0, s72
	ds_read_b128 v[190:193], v166 offset:16384
	ds_read_b128 v[194:197], v166 offset:17408
	ds_read_b128 v[198:201], v166 offset:18432
	ds_read_b128 v[202:205], v166 offset:19456
	ds_read_b128 v[206:209], v166 offset:20480
	ds_read_b128 v[210:213], v166 offset:21504
	ds_read_b128 v[214:217], v166 offset:22528
	ds_read_b128 v[218:221], v166 offset:23552
	global_load_lds_dwordx4 v[160:161], off
	s_add_i32 m0, s72, 0x2000
	s_add_u32 s72, s48, 0x40000
	v_lshl_add_u64 v[222:223], s[48:49], 0, v[138:139]
	s_addc_u32 s73, s49, 0
	s_add_i32 s80, s77, s62
	global_load_lds_dwordx4 v[222:223], off
	s_mov_b32 m0, s80
	v_lshl_add_u64 v[226:227], s[52:53], 0, v[140:141]
	global_load_lds_dwordx4 v142, s[72:73]
	s_add_i32 m0, s80, 0x2000
	s_nop 0
	global_load_lds_dwordx4 v138, s[72:73]
	v_lshl_add_u64 v[224:225], s[52:53], 0, v[144:145]
	s_mov_b32 m0, s43
	s_nop 0
	global_load_lds_dwordx4 v[224:225], off
	s_mov_b32 m0, s63
	s_nop 0
	global_load_lds_dwordx4 v[226:227], off
	s_waitcnt vmcnt(8)
	s_waitcnt lgkmcnt(0)
	s_barrier
	s_setprio 1
	s_waitcnt lgkmcnt(0)
	v_mfma_f32_16x16x32_bf16 v[62:65], v[130:133], v[190:193], v[62:65]
	v_mfma_f32_16x16x32_bf16 v[58:61], v[156:159], v[190:193], v[58:61]
	v_mfma_f32_16x16x32_bf16 v[46:49], v[130:133], v[198:201], v[46:49]
	v_mfma_f32_16x16x32_bf16 v[42:45], v[156:159], v[198:201], v[42:45]
	v_mfma_f32_16x16x32_bf16 v[30:33], v[130:133], v[206:209], v[30:33]
	v_mfma_f32_16x16x32_bf16 v[26:29], v[156:159], v[206:209], v[26:29]
	v_mfma_f32_16x16x32_bf16 v[14:17], v[130:133], v[214:217], v[14:17]
	v_mfma_f32_16x16x32_bf16 v[10:13], v[156:159], v[214:217], v[10:13]
	v_mfma_f32_16x16x32_bf16 v[62:65], v[134:137], v[194:197], v[62:65]
	v_mfma_f32_16x16x32_bf16 v[58:61], v[168:171], v[194:197], v[58:61]
	v_mfma_f32_16x16x32_bf16 v[46:49], v[134:137], v[202:205], v[46:49]
	v_mfma_f32_16x16x32_bf16 v[42:45], v[168:171], v[202:205], v[42:45]
	v_mfma_f32_16x16x32_bf16 v[30:33], v[134:137], v[210:213], v[30:33]
	v_mfma_f32_16x16x32_bf16 v[26:29], v[168:171], v[210:213], v[26:29]
	v_mfma_f32_16x16x32_bf16 v[14:17], v[134:137], v[218:221], v[14:17]
	v_mfma_f32_16x16x32_bf16 v[10:13], v[168:171], v[218:221], v[10:13]
	s_setprio 0
	s_setprio 1
	v_mfma_f32_16x16x32_bf16 v[54:57], v[172:175], v[190:193], v[54:57]
	v_mfma_f32_16x16x32_bf16 v[50:53], v[182:185], v[190:193], v[50:53]
	v_mfma_f32_16x16x32_bf16 v[38:41], v[172:175], v[198:201], v[38:41]
	v_mfma_f32_16x16x32_bf16 v[34:37], v[182:185], v[198:201], v[34:37]
	v_mfma_f32_16x16x32_bf16 v[22:25], v[172:175], v[206:209], v[22:25]
	v_mfma_f32_16x16x32_bf16 v[18:21], v[182:185], v[206:209], v[18:21]
	v_mfma_f32_16x16x32_bf16 v[6:9], v[172:175], v[214:217], v[6:9]
	v_mfma_f32_16x16x32_bf16 v[2:5], v[182:185], v[214:217], v[2:5]
	v_mfma_f32_16x16x32_bf16 v[54:57], v[178:181], v[194:197], v[54:57]
	v_mfma_f32_16x16x32_bf16 v[50:53], v[186:189], v[194:197], v[50:53]
	v_mfma_f32_16x16x32_bf16 v[38:41], v[178:181], v[202:205], v[38:41]
	v_mfma_f32_16x16x32_bf16 v[34:37], v[186:189], v[202:205], v[34:37]
	v_mfma_f32_16x16x32_bf16 v[22:25], v[178:181], v[210:213], v[22:25]
	v_mfma_f32_16x16x32_bf16 v[18:21], v[186:189], v[210:213], v[18:21]
	v_mfma_f32_16x16x32_bf16 v[6:9], v[178:181], v[218:221], v[6:9]
	v_mfma_f32_16x16x32_bf16 v[2:5], v[186:189], v[218:221], v[2:5]
	s_setprio 0
	s_barrier
	s_add_i32 s72, 0, 0x18000
	v_add_u32_e32 v167, s72, v162
	s_add_i32 s73, 0, 0x1c000
	ds_read_b128 v[130:133], v167
	ds_read_b128 v[134:137], v167 offset:1024
	ds_read_b128 v[156:159], v167 offset:2048
	ds_read_b128 v[168:171], v167 offset:3072
	v_add_u32_e32 v167, s73, v162
	ds_read_b128 v[172:175], v167
	ds_read_b128 v[178:181], v167 offset:1024
	ds_read_b128 v[182:185], v167 offset:2048
	ds_read_b128 v[186:189], v167 offset:3072
	s_add_u32 s52, s52, 0x40000
	s_addc_u32 s53, s53, 0
	s_mov_b32 m0, s64
	ds_read_b128 v[190:193], v166 offset:32768
	ds_read_b128 v[194:197], v166 offset:33792
	ds_read_b128 v[198:201], v166 offset:34816
	ds_read_b128 v[202:205], v166 offset:35840
	ds_read_b128 v[206:209], v166 offset:36864
	ds_read_b128 v[210:213], v166 offset:37888
	ds_read_b128 v[214:217], v166 offset:38912
	ds_read_b128 v[218:221], v166 offset:39936
	global_load_lds_dwordx4 v144, s[52:53]
	s_mov_b32 m0, s65
	s_nop 0
	global_load_lds_dwordx4 v140, s[52:53]
	s_waitcnt vmcnt(8)
	s_waitcnt lgkmcnt(0)
	s_barrier
	s_setprio 1
	s_waitcnt lgkmcnt(0)
	v_mfma_f32_16x16x32_bf16 v[126:129], v[130:133], v[190:193], v[126:129]
	v_mfma_f32_16x16x32_bf16 v[122:125], v[156:159], v[190:193], v[122:125]
	v_mfma_f32_16x16x32_bf16 v[110:113], v[130:133], v[198:201], v[110:113]
	v_mfma_f32_16x16x32_bf16 v[106:109], v[156:159], v[198:201], v[106:109]
	v_mfma_f32_16x16x32_bf16 v[94:97], v[130:133], v[206:209], v[94:97]
	v_mfma_f32_16x16x32_bf16 v[90:93], v[156:159], v[206:209], v[90:93]
	v_mfma_f32_16x16x32_bf16 v[78:81], v[130:133], v[214:217], v[78:81]
	v_mfma_f32_16x16x32_bf16 v[74:77], v[156:159], v[214:217], v[74:77]
	v_mfma_f32_16x16x32_bf16 v[126:129], v[134:137], v[194:197], v[126:129]
	v_mfma_f32_16x16x32_bf16 v[122:125], v[168:171], v[194:197], v[122:125]
	v_mfma_f32_16x16x32_bf16 v[110:113], v[134:137], v[202:205], v[110:113]
	v_mfma_f32_16x16x32_bf16 v[106:109], v[168:171], v[202:205], v[106:109]
	v_mfma_f32_16x16x32_bf16 v[94:97], v[134:137], v[210:213], v[94:97]
	v_mfma_f32_16x16x32_bf16 v[90:93], v[168:171], v[210:213], v[90:93]
	v_mfma_f32_16x16x32_bf16 v[78:81], v[134:137], v[218:221], v[78:81]
	v_mfma_f32_16x16x32_bf16 v[74:77], v[168:171], v[218:221], v[74:77]
	s_setprio 0
	s_setprio 1
	v_mfma_f32_16x16x32_bf16 v[118:121], v[172:175], v[190:193], v[118:121]
	v_mfma_f32_16x16x32_bf16 v[114:117], v[182:185], v[190:193], v[114:117]
	v_mfma_f32_16x16x32_bf16 v[102:105], v[172:175], v[198:201], v[102:105]
	v_mfma_f32_16x16x32_bf16 v[98:101], v[182:185], v[198:201], v[98:101]
	v_mfma_f32_16x16x32_bf16 v[86:89], v[172:175], v[206:209], v[86:89]
	v_mfma_f32_16x16x32_bf16 v[82:85], v[182:185], v[206:209], v[82:85]
	v_mfma_f32_16x16x32_bf16 v[70:73], v[172:175], v[214:217], v[70:73]
	v_mfma_f32_16x16x32_bf16 v[66:69], v[182:185], v[214:217], v[66:69]
	v_mfma_f32_16x16x32_bf16 v[118:121], v[178:181], v[194:197], v[118:121]
	v_mfma_f32_16x16x32_bf16 v[114:117], v[186:189], v[194:197], v[114:117]
	v_mfma_f32_16x16x32_bf16 v[102:105], v[178:181], v[202:205], v[102:105]
	v_mfma_f32_16x16x32_bf16 v[98:101], v[186:189], v[202:205], v[98:101]
	v_mfma_f32_16x16x32_bf16 v[86:89], v[178:181], v[210:213], v[86:89]
	v_mfma_f32_16x16x32_bf16 v[82:85], v[186:189], v[210:213], v[82:85]
	v_mfma_f32_16x16x32_bf16 v[70:73], v[178:181], v[218:221], v[70:73]
	v_mfma_f32_16x16x32_bf16 v[66:69], v[186:189], v[218:221], v[66:69]
	s_setprio 0
	s_barrier
	s_add_i32 s52, s72, s62
	v_lshl_add_u64 v[160:161], v[160:161], 0, s[18:19]
	s_mov_b32 m0, s52
	ds_read_b128 v[190:193], v166 offset:49152
	ds_read_b128 v[194:197], v166 offset:50176
	ds_read_b128 v[198:201], v166 offset:51200
	ds_read_b128 v[202:205], v166 offset:52224
	ds_read_b128 v[206:209], v166 offset:53248
	ds_read_b128 v[210:213], v166 offset:54272
	ds_read_b128 v[214:217], v166 offset:55296
	ds_read_b128 v[218:221], v166 offset:56320
	global_load_lds_dwordx4 v[160:161], off
	s_add_i32 m0, s52, 0x2000
	s_add_u32 s48, s48, 0x40080
	v_lshl_add_u64 v[160:161], v[222:223], 0, s[18:19]
	s_addc_u32 s49, s49, 0
	s_add_i32 s52, s73, s62
	global_load_lds_dwordx4 v[160:161], off
	s_mov_b32 m0, s52
	s_nop 0
	global_load_lds_dwordx4 v142, s[48:49]
	s_add_i32 m0, s52, 0x2000
	s_nop 0
	global_load_lds_dwordx4 v138, s[48:49]
	v_lshl_add_u64 v[160:161], v[224:225], 0, s[18:19]
	s_mov_b32 m0, s66
	s_nop 0
	global_load_lds_dwordx4 v[160:161], off
	v_lshl_add_u64 v[160:161], v[226:227], 0, s[18:19]
	s_mov_b32 m0, s67
	s_nop 0
	global_load_lds_dwordx4 v[160:161], off
	s_waitcnt vmcnt(8)
	s_waitcnt lgkmcnt(0)
	s_barrier
	s_setprio 1
	s_waitcnt lgkmcnt(0)
	v_mfma_f32_16x16x32_bf16 v[62:65], v[130:133], v[190:193], v[62:65]
	v_mfma_f32_16x16x32_bf16 v[58:61], v[156:159], v[190:193], v[58:61]
	v_mfma_f32_16x16x32_bf16 v[46:49], v[130:133], v[198:201], v[46:49]
	v_mfma_f32_16x16x32_bf16 v[42:45], v[156:159], v[198:201], v[42:45]
	v_mfma_f32_16x16x32_bf16 v[30:33], v[130:133], v[206:209], v[30:33]
	v_mfma_f32_16x16x32_bf16 v[26:29], v[156:159], v[206:209], v[26:29]
	v_mfma_f32_16x16x32_bf16 v[14:17], v[130:133], v[214:217], v[14:17]
	v_mfma_f32_16x16x32_bf16 v[10:13], v[156:159], v[214:217], v[10:13]
	v_mfma_f32_16x16x32_bf16 v[62:65], v[134:137], v[194:197], v[62:65]
	v_mfma_f32_16x16x32_bf16 v[58:61], v[168:171], v[194:197], v[58:61]
	v_mfma_f32_16x16x32_bf16 v[46:49], v[134:137], v[202:205], v[46:49]
	v_mfma_f32_16x16x32_bf16 v[42:45], v[168:171], v[202:205], v[42:45]
	v_mfma_f32_16x16x32_bf16 v[30:33], v[134:137], v[210:213], v[30:33]
	v_mfma_f32_16x16x32_bf16 v[26:29], v[168:171], v[210:213], v[26:29]
	v_mfma_f32_16x16x32_bf16 v[14:17], v[134:137], v[218:221], v[14:17]
	v_mfma_f32_16x16x32_bf16 v[10:13], v[168:171], v[218:221], v[10:13]
	s_setprio 0
	s_setprio 1
	v_mfma_f32_16x16x32_bf16 v[54:57], v[172:175], v[190:193], v[54:57]
	v_mfma_f32_16x16x32_bf16 v[50:53], v[182:185], v[190:193], v[50:53]
	v_mfma_f32_16x16x32_bf16 v[38:41], v[172:175], v[198:201], v[38:41]
	v_mfma_f32_16x16x32_bf16 v[34:37], v[182:185], v[198:201], v[34:37]
	v_mfma_f32_16x16x32_bf16 v[22:25], v[172:175], v[206:209], v[22:25]
	v_mfma_f32_16x16x32_bf16 v[18:21], v[182:185], v[206:209], v[18:21]
	v_mfma_f32_16x16x32_bf16 v[6:9], v[172:175], v[214:217], v[6:9]
	v_mfma_f32_16x16x32_bf16 v[2:5], v[182:185], v[214:217], v[2:5]
	v_mfma_f32_16x16x32_bf16 v[54:57], v[178:181], v[194:197], v[54:57]
	v_mfma_f32_16x16x32_bf16 v[50:53], v[186:189], v[194:197], v[50:53]
	v_mfma_f32_16x16x32_bf16 v[38:41], v[178:181], v[202:205], v[38:41]
	v_mfma_f32_16x16x32_bf16 v[34:37], v[186:189], v[202:205], v[34:37]
	v_mfma_f32_16x16x32_bf16 v[22:25], v[178:181], v[210:213], v[22:25]
	v_mfma_f32_16x16x32_bf16 v[18:21], v[186:189], v[210:213], v[18:21]
	v_mfma_f32_16x16x32_bf16 v[6:9], v[178:181], v[218:221], v[6:9]
	v_mfma_f32_16x16x32_bf16 v[2:5], v[186:189], v[218:221], v[2:5]
	s_setprio 0
	s_barrier
	s_add_i32 s79, s79, 2
	s_add_u32 s44, s44, 0x100
	s_addc_u32 s45, s45, 0
	s_add_u32 s75, s75, 0x100
	s_addc_u32 s78, s78, 0
	s_cmp_gt_u32 s79, 13
	s_cbranch_scc0 .LBB0_783
	s_and_b64 vcc, exec, s[20:21]
	s_cbranch_vccz .LBB0_786
	s_barrier

.LBB0_803:
	ds_read_b128 v[130:133], v174
	ds_read_b128 v[134:137], v174 offset:1024
	ds_read_b128 v[138:141], v174 offset:2048
	ds_read_b128 v[142:145], v174 offset:3072
	ds_read_b128 v[164:167], v175
	ds_read_b128 v[168:171], v175 offset:1024
	ds_read_b128 v[178:181], v175 offset:2048
	ds_read_b128 v[182:185], v175 offset:3072
	s_add_u32 s42, s40, 0xfffc0080
	s_addc_u32 s43, s41, -1
	s_cmp_eq_u32 s67, 12
	s_cselect_b32 s45, s13, s43
	s_cselect_b32 s44, s21, s42
	s_cselect_b32 s43, s19, s66
	s_cselect_b32 s42, s64, s65
	s_add_i32 m0, s39, 0xc000
	ds_read_b128 v[186:189], v177
	ds_read_b128 v[190:193], v177 offset:1024
	ds_read_b128 v[194:197], v177 offset:2048
	ds_read_b128 v[198:201], v177 offset:3072
	ds_read_b128 v[202:205], v177 offset:4096
	ds_read_b128 v[206:209], v177 offset:5120
	ds_read_b128 v[210:213], v177 offset:6144
	ds_read_b128 v[214:217], v177 offset:7168
	global_load_lds_dwordx4 v156, s[40:41]
	s_add_i32 m0, s39, 0xe000
	s_nop 0
	global_load_lds_dwordx4 v158, s[40:41]
	s_waitcnt vmcnt(8)
	s_waitcnt lgkmcnt(0)
	s_barrier
	s_setprio 1
	s_waitcnt lgkmcnt(0)
	v_mfma_f32_16x16x32_bf16 v[126:129], v[130:133], v[186:189], v[126:129]
	v_mfma_f32_16x16x32_bf16 v[122:125], v[138:141], v[186:189], v[122:125]
	v_mfma_f32_16x16x32_bf16 v[110:113], v[130:133], v[194:197], v[110:113]
	v_mfma_f32_16x16x32_bf16 v[106:109], v[138:141], v[194:197], v[106:109]
	v_mfma_f32_16x16x32_bf16 v[94:97], v[130:133], v[202:205], v[94:97]
	v_mfma_f32_16x16x32_bf16 v[90:93], v[138:141], v[202:205], v[90:93]
	v_mfma_f32_16x16x32_bf16 v[78:81], v[130:133], v[210:213], v[78:81]
	v_mfma_f32_16x16x32_bf16 v[74:77], v[138:141], v[210:213], v[74:77]
	v_mfma_f32_16x16x32_bf16 v[126:129], v[134:137], v[190:193], v[126:129]
	v_mfma_f32_16x16x32_bf16 v[122:125], v[142:145], v[190:193], v[122:125]
	v_mfma_f32_16x16x32_bf16 v[110:113], v[134:137], v[198:201], v[110:113]
	v_mfma_f32_16x16x32_bf16 v[106:109], v[142:145], v[198:201], v[106:109]
	v_mfma_f32_16x16x32_bf16 v[94:97], v[134:137], v[206:209], v[94:97]
	v_mfma_f32_16x16x32_bf16 v[90:93], v[142:145], v[206:209], v[90:93]
	v_mfma_f32_16x16x32_bf16 v[78:81], v[134:137], v[214:217], v[78:81]
	v_mfma_f32_16x16x32_bf16 v[74:77], v[142:145], v[214:217], v[74:77]
	s_setprio 0
	s_setprio 1
	v_mfma_f32_16x16x32_bf16 v[118:121], v[164:167], v[186:189], v[118:121]
	v_mfma_f32_16x16x32_bf16 v[114:117], v[178:181], v[186:189], v[114:117]
	v_mfma_f32_16x16x32_bf16 v[102:105], v[164:167], v[194:197], v[102:105]
	v_mfma_f32_16x16x32_bf16 v[98:101], v[178:181], v[194:197], v[98:101]
	v_mfma_f32_16x16x32_bf16 v[86:89], v[164:167], v[202:205], v[86:89]
	v_mfma_f32_16x16x32_bf16 v[82:85], v[178:181], v[202:205], v[82:85]
	v_mfma_f32_16x16x32_bf16 v[70:73], v[164:167], v[210:213], v[70:73]
	v_mfma_f32_16x16x32_bf16 v[66:69], v[178:181], v[210:213], v[66:69]
	v_mfma_f32_16x16x32_bf16 v[118:121], v[168:171], v[190:193], v[118:121]
	v_mfma_f32_16x16x32_bf16 v[114:117], v[182:185], v[190:193], v[114:117]
	v_mfma_f32_16x16x32_bf16 v[102:105], v[168:171], v[198:201], v[102:105]
	v_mfma_f32_16x16x32_bf16 v[98:101], v[182:185], v[198:201], v[98:101]
	v_mfma_f32_16x16x32_bf16 v[86:89], v[168:171], v[206:209], v[86:89]
	v_mfma_f32_16x16x32_bf16 v[82:85], v[182:185], v[206:209], v[82:85]
	v_mfma_f32_16x16x32_bf16 v[70:73], v[168:171], v[214:217], v[70:73]
	v_mfma_f32_16x16x32_bf16 v[66:69], v[182:185], v[214:217], v[66:69]
	s_setprio 0
	s_barrier
	s_add_i32 s69, s62, s48
	v_lshl_add_u64 v[218:219], s[42:43], 0, v[152:153]
	s_mov_b32 m0, s69
	ds_read_b128 v[186:189], v177 offset:16384
	ds_read_b128 v[190:193], v177 offset:17408
	ds_read_b128 v[194:197], v177 offset:18432
	ds_read_b128 v[198:201], v177 offset:19456
	ds_read_b128 v[202:205], v177 offset:20480
	ds_read_b128 v[206:209], v177 offset:21504
	ds_read_b128 v[210:213], v177 offset:22528
	ds_read_b128 v[214:217], v177 offset:23552
	global_load_lds_dwordx4 v[218:219], off
	s_add_i32 m0, s69, 0x2000
	s_add_u32 s72, s42, 0x40000
	v_lshl_add_u64 v[220:221], s[42:43], 0, v[148:149]
	s_addc_u32 s73, s43, 0
	s_add_i32 s69, s63, s48
	global_load_lds_dwordx4 v[220:221], off
	s_mov_b32 m0, s69
	v_lshl_add_u64 v[224:225], s[44:45], 0, v[150:151]
	global_load_lds_dwordx4 v152, s[72:73]
	s_add_i32 m0, s69, 0x2000
	s_nop 0
	global_load_lds_dwordx4 v148, s[72:73]
	v_lshl_add_u64 v[222:223], s[44:45], 0, v[154:155]
	s_mov_b32 m0, s39
	s_nop 0
	global_load_lds_dwordx4 v[222:223], off
	s_mov_b32 m0, s56
	s_nop 0
	global_load_lds_dwordx4 v[224:225], off
	s_waitcnt vmcnt(8)
	s_waitcnt lgkmcnt(0)
	s_barrier
	s_setprio 1
	s_waitcnt lgkmcnt(0)
	v_mfma_f32_16x16x32_bf16 v[62:65], v[130:133], v[186:189], v[62:65]
	v_mfma_f32_16x16x32_bf16 v[58:61], v[138:141], v[186:189], v[58:61]
	v_mfma_f32_16x16x32_bf16 v[46:49], v[130:133], v[194:197], v[46:49]
	v_mfma_f32_16x16x32_bf16 v[42:45], v[138:141], v[194:197], v[42:45]
	v_mfma_f32_16x16x32_bf16 v[30:33], v[130:133], v[202:205], v[30:33]
	v_mfma_f32_16x16x32_bf16 v[26:29], v[138:141], v[202:205], v[26:29]
	v_mfma_f32_16x16x32_bf16 v[14:17], v[130:133], v[210:213], v[14:17]
	v_mfma_f32_16x16x32_bf16 v[10:13], v[138:141], v[210:213], v[10:13]
	v_mfma_f32_16x16x32_bf16 v[62:65], v[134:137], v[190:193], v[62:65]
	v_mfma_f32_16x16x32_bf16 v[58:61], v[142:145], v[190:193], v[58:61]
	v_mfma_f32_16x16x32_bf16 v[46:49], v[134:137], v[198:201], v[46:49]
	v_mfma_f32_16x16x32_bf16 v[42:45], v[142:145], v[198:201], v[42:45]
	v_mfma_f32_16x16x32_bf16 v[30:33], v[134:137], v[206:209], v[30:33]
	v_mfma_f32_16x16x32_bf16 v[26:29], v[142:145], v[206:209], v[26:29]
	v_mfma_f32_16x16x32_bf16 v[14:17], v[134:137], v[214:217], v[14:17]
	v_mfma_f32_16x16x32_bf16 v[10:13], v[142:145], v[214:217], v[10:13]
	s_setprio 0
	s_setprio 1
	v_mfma_f32_16x16x32_bf16 v[54:57], v[164:167], v[186:189], v[54:57]
	v_mfma_f32_16x16x32_bf16 v[50:53], v[178:181], v[186:189], v[50:53]
	v_mfma_f32_16x16x32_bf16 v[38:41], v[164:167], v[194:197], v[38:41]
	v_mfma_f32_16x16x32_bf16 v[34:37], v[178:181], v[194:197], v[34:37]
	v_mfma_f32_16x16x32_bf16 v[22:25], v[164:167], v[202:205], v[22:25]
	v_mfma_f32_16x16x32_bf16 v[18:21], v[178:181], v[202:205], v[18:21]
	v_mfma_f32_16x16x32_bf16 v[6:9], v[164:167], v[210:213], v[6:9]
	v_mfma_f32_16x16x32_bf16 v[2:5], v[178:181], v[210:213], v[2:5]
	v_mfma_f32_16x16x32_bf16 v[54:57], v[168:171], v[190:193], v[54:57]
	v_mfma_f32_16x16x32_bf16 v[50:53], v[182:185], v[190:193], v[50:53]
	v_mfma_f32_16x16x32_bf16 v[38:41], v[168:171], v[198:201], v[38:41]
	v_mfma_f32_16x16x32_bf16 v[34:37], v[182:185], v[198:201], v[34:37]
	v_mfma_f32_16x16x32_bf16 v[22:25], v[168:171], v[206:209], v[22:25]
	v_mfma_f32_16x16x32_bf16 v[18:21], v[182:185], v[206:209], v[18:21]
	v_mfma_f32_16x16x32_bf16 v[6:9], v[168:171], v[214:217], v[6:9]
	v_mfma_f32_16x16x32_bf16 v[2:5], v[182:185], v[214:217], v[2:5]
	s_setprio 0
	s_barrier
	s_add_i32 s69, 0, 0x18000
	s_add_i32 s72, 0, 0x1c000
	v_add_u32_e32 v142, s69, v172
	v_add_u32_e32 v182, s72, v172
	ds_read_b128 v[130:133], v142
	ds_read_b128 v[134:137], v142 offset:1024
	ds_read_b128 v[138:141], v142 offset:2048
	ds_read_b128 v[142:145], v142 offset:3072
	ds_read_b128 v[164:167], v182
	ds_read_b128 v[168:171], v182 offset:1024
	ds_read_b128 v[178:181], v182 offset:2048
	ds_read_b128 v[182:185], v182 offset:3072
	s_add_u32 s44, s44, 0x40000
	s_addc_u32 s45, s45, 0
	s_mov_b32 m0, s57
	ds_read_b128 v[186:189], v177 offset:32768
	ds_read_b128 v[190:193], v177 offset:33792
	ds_read_b128 v[194:197], v177 offset:34816
	ds_read_b128 v[198:201], v177 offset:35840
	ds_read_b128 v[202:205], v177 offset:36864
	ds_read_b128 v[206:209], v177 offset:37888
	ds_read_b128 v[210:213], v177 offset:38912
	ds_read_b128 v[214:217], v177 offset:39936
	global_load_lds_dwordx4 v154, s[44:45]
	s_mov_b32 m0, s58
	s_nop 0
	global_load_lds_dwordx4 v150, s[44:45]
	s_waitcnt vmcnt(8)
	s_waitcnt lgkmcnt(0)
	s_barrier
	s_setprio 1
	s_waitcnt lgkmcnt(0)
	v_mfma_f32_16x16x32_bf16 v[126:129], v[130:133], v[186:189], v[126:129]
	v_mfma_f32_16x16x32_bf16 v[122:125], v[138:141], v[186:189], v[122:125]
	v_mfma_f32_16x16x32_bf16 v[110:113], v[130:133], v[194:197], v[110:113]
	v_mfma_f32_16x16x32_bf16 v[106:109], v[138:141], v[194:197], v[106:109]
	v_mfma_f32_16x16x32_bf16 v[94:97], v[130:133], v[202:205], v[94:97]
	v_mfma_f32_16x16x32_bf16 v[90:93], v[138:141], v[202:205], v[90:93]
	v_mfma_f32_16x16x32_bf16 v[78:81], v[130:133], v[210:213], v[78:81]
	v_mfma_f32_16x16x32_bf16 v[74:77], v[138:141], v[210:213], v[74:77]
	v_mfma_f32_16x16x32_bf16 v[126:129], v[134:137], v[190:193], v[126:129]
	v_mfma_f32_16x16x32_bf16 v[122:125], v[142:145], v[190:193], v[122:125]
	v_mfma_f32_16x16x32_bf16 v[110:113], v[134:137], v[198:201], v[110:113]
	v_mfma_f32_16x16x32_bf16 v[106:109], v[142:145], v[198:201], v[106:109]
	v_mfma_f32_16x16x32_bf16 v[94:97], v[134:137], v[206:209], v[94:97]
	v_mfma_f32_16x16x32_bf16 v[90:93], v[142:145], v[206:209], v[90:93]
	v_mfma_f32_16x16x32_bf16 v[78:81], v[134:137], v[214:217], v[78:81]
	v_mfma_f32_16x16x32_bf16 v[74:77], v[142:145], v[214:217], v[74:77]
	s_setprio 0
	s_setprio 1
	v_mfma_f32_16x16x32_bf16 v[118:121], v[164:167], v[186:189], v[118:121]
	v_mfma_f32_16x16x32_bf16 v[114:117], v[178:181], v[186:189], v[114:117]
	v_mfma_f32_16x16x32_bf16 v[102:105], v[164:167], v[194:197], v[102:105]
	v_mfma_f32_16x16x32_bf16 v[98:101], v[178:181], v[194:197], v[98:101]
	v_mfma_f32_16x16x32_bf16 v[86:89], v[164:167], v[202:205], v[86:89]
	v_mfma_f32_16x16x32_bf16 v[82:85], v[178:181], v[202:205], v[82:85]
	v_mfma_f32_16x16x32_bf16 v[70:73], v[164:167], v[210:213], v[70:73]
	v_mfma_f32_16x16x32_bf16 v[66:69], v[178:181], v[210:213], v[66:69]
	v_mfma_f32_16x16x32_bf16 v[118:121], v[168:171], v[190:193], v[118:121]
	v_mfma_f32_16x16x32_bf16 v[114:117], v[182:185], v[190:193], v[114:117]
	v_mfma_f32_16x16x32_bf16 v[102:105], v[168:171], v[198:201], v[102:105]
	v_mfma_f32_16x16x32_bf16 v[98:101], v[182:185], v[198:201], v[98:101]
	v_mfma_f32_16x16x32_bf16 v[86:89], v[168:171], v[206:209], v[86:89]
	v_mfma_f32_16x16x32_bf16 v[82:85], v[182:185], v[206:209], v[82:85]
	v_mfma_f32_16x16x32_bf16 v[70:73], v[168:171], v[214:217], v[70:73]
	v_mfma_f32_16x16x32_bf16 v[66:69], v[182:185], v[214:217], v[66:69]
	s_setprio 0
	s_barrier
	s_add_i32 s44, s69, s48
	v_lshl_add_u64 v[218:219], v[218:219], 0, s[10:11]
	s_mov_b32 m0, s44
	ds_read_b128 v[186:189], v177 offset:49152
	ds_read_b128 v[190:193], v177 offset:50176
	ds_read_b128 v[194:197], v177 offset:51200
	ds_read_b128 v[198:201], v177 offset:52224
	ds_read_b128 v[202:205], v177 offset:53248
	ds_read_b128 v[206:209], v177 offset:54272
	ds_read_b128 v[210:213], v177 offset:55296
	ds_read_b128 v[214:217], v177 offset:56320
	global_load_lds_dwordx4 v[218:219], off
	s_add_i32 m0, s44, 0x2000
	s_add_u32 s42, s42, 0x40080
	v_lshl_add_u64 v[218:219], v[220:221], 0, s[10:11]
	s_addc_u32 s43, s43, 0
	s_add_i32 s44, s72, s48
	global_load_lds_dwordx4 v[218:219], off
	s_mov_b32 m0, s44
	s_nop 0
	global_load_lds_dwordx4 v152, s[42:43]
	s_add_i32 m0, s44, 0x2000
	s_nop 0
	global_load_lds_dwordx4 v148, s[42:43]
	v_lshl_add_u64 v[218:219], v[222:223], 0, s[10:11]
	s_mov_b32 m0, s60
	s_nop 0
	global_load_lds_dwordx4 v[218:219], off
	v_lshl_add_u64 v[218:219], v[224:225], 0, s[10:11]
	s_mov_b32 m0, s61
	s_nop 0
	global_load_lds_dwordx4 v[218:219], off
	s_waitcnt vmcnt(8)
	s_waitcnt lgkmcnt(0)
	s_barrier
	s_setprio 1
	s_waitcnt lgkmcnt(0)
	v_mfma_f32_16x16x32_bf16 v[62:65], v[130:133], v[186:189], v[62:65]
	v_mfma_f32_16x16x32_bf16 v[58:61], v[138:141], v[186:189], v[58:61]
	v_mfma_f32_16x16x32_bf16 v[46:49], v[130:133], v[194:197], v[46:49]
	v_mfma_f32_16x16x32_bf16 v[42:45], v[138:141], v[194:197], v[42:45]
	v_mfma_f32_16x16x32_bf16 v[30:33], v[130:133], v[202:205], v[30:33]
	v_mfma_f32_16x16x32_bf16 v[26:29], v[138:141], v[202:205], v[26:29]
	v_mfma_f32_16x16x32_bf16 v[14:17], v[130:133], v[210:213], v[14:17]
	v_mfma_f32_16x16x32_bf16 v[10:13], v[138:141], v[210:213], v[10:13]
	v_mfma_f32_16x16x32_bf16 v[62:65], v[134:137], v[190:193], v[62:65]
	v_mfma_f32_16x16x32_bf16 v[58:61], v[142:145], v[190:193], v[58:61]
	v_mfma_f32_16x16x32_bf16 v[46:49], v[134:137], v[198:201], v[46:49]
	v_mfma_f32_16x16x32_bf16 v[42:45], v[142:145], v[198:201], v[42:45]
	v_mfma_f32_16x16x32_bf16 v[30:33], v[134:137], v[206:209], v[30:33]
	v_mfma_f32_16x16x32_bf16 v[26:29], v[142:145], v[206:209], v[26:29]
	v_mfma_f32_16x16x32_bf16 v[14:17], v[134:137], v[214:217], v[14:17]
	v_mfma_f32_16x16x32_bf16 v[10:13], v[142:145], v[214:217], v[10:13]
	s_setprio 0
	s_setprio 1
	v_mfma_f32_16x16x32_bf16 v[54:57], v[164:167], v[186:189], v[54:57]
	v_mfma_f32_16x16x32_bf16 v[50:53], v[178:181], v[186:189], v[50:53]
	v_mfma_f32_16x16x32_bf16 v[38:41], v[164:167], v[194:197], v[38:41]
	v_mfma_f32_16x16x32_bf16 v[34:37], v[178:181], v[194:197], v[34:37]
	v_mfma_f32_16x16x32_bf16 v[22:25], v[164:167], v[202:205], v[22:25]
	v_mfma_f32_16x16x32_bf16 v[18:21], v[178:181], v[202:205], v[18:21]
	v_mfma_f32_16x16x32_bf16 v[6:9], v[164:167], v[210:213], v[6:9]
	v_mfma_f32_16x16x32_bf16 v[2:5], v[178:181], v[210:213], v[2:5]
	v_mfma_f32_16x16x32_bf16 v[54:57], v[168:171], v[190:193], v[54:57]
	v_mfma_f32_16x16x32_bf16 v[50:53], v[182:185], v[190:193], v[50:53]
	v_mfma_f32_16x16x32_bf16 v[38:41], v[168:171], v[198:201], v[38:41]
	v_mfma_f32_16x16x32_bf16 v[34:37], v[182:185], v[198:201], v[34:37]
	v_mfma_f32_16x16x32_bf16 v[22:25], v[168:171], v[206:209], v[22:25]
	v_mfma_f32_16x16x32_bf16 v[18:21], v[182:185], v[206:209], v[18:21]
	v_mfma_f32_16x16x32_bf16 v[6:9], v[168:171], v[214:217], v[6:9]
	v_mfma_f32_16x16x32_bf16 v[2:5], v[182:185], v[214:217], v[2:5]
	s_setprio 0
	s_barrier
	s_add_i32 s67, s67, 2
	s_add_u32 s40, s40, 0x100
	s_addc_u32 s41, s41, 0
	s_add_u32 s65, s65, 0x100
	s_addc_u32 s66, s66, 0
	s_cmp_gt_u32 s67, 13
	s_cbranch_scc0 .LBB0_803
	s_and_b64 vcc, exec, s[16:17]
	s_cbranch_vccz .LBB0_806
	s_barrier

.LBB0_890:
	ds_read_b128 v[142:145], v166
	ds_read_b128 v[148:151], v166 offset:1024
	ds_read_b128 v[152:155], v166 offset:2048
	ds_read_b128 v[156:159], v166 offset:3072
	ds_read_b128 v[160:163], v167
	ds_read_b128 v[172:175], v167 offset:1024
	ds_read_b128 v[178:181], v167 offset:2048
	ds_read_b128 v[182:185], v167 offset:3072
	s_add_u32 s42, s40, 0xfff80080
	s_addc_u32 s43, s41, -1
	s_cmp_eq_u32 s82, 28
	s_cselect_b32 s45, s13, s43
	s_cselect_b32 s44, s21, s42
	s_cselect_b32 s43, s19, s81
	s_cselect_b32 s42, s74, s75
	s_add_i32 m0, s39, 0xc000
	ds_read_b128 v[186:189], v168
	ds_read_b128 v[190:193], v168 offset:1024
	ds_read_b128 v[194:197], v168 offset:2048
	ds_read_b128 v[198:201], v168 offset:3072
	ds_read_b128 v[202:205], v168 offset:4096
	ds_read_b128 v[206:209], v168 offset:5120
	ds_read_b128 v[210:213], v168 offset:6144
	ds_read_b128 v[214:217], v168 offset:7168
	global_load_lds_dwordx4 v134, s[40:41]
	s_add_i32 m0, s39, 0xe000
	s_nop 0
	global_load_lds_dwordx4 v136, s[40:41]
	s_waitcnt vmcnt(8)
	s_waitcnt lgkmcnt(0)
	s_barrier
	s_setprio 1
	s_waitcnt lgkmcnt(0)
	v_mfma_f32_16x16x32_bf16 v[122:125], v[142:145], v[186:189], v[122:125]
	v_mfma_f32_16x16x32_bf16 v[126:129], v[152:155], v[186:189], v[126:129]
	v_mfma_f32_16x16x32_bf16 v[114:117], v[142:145], v[194:197], v[114:117]
	v_mfma_f32_16x16x32_bf16 v[118:121], v[152:155], v[194:197], v[118:121]
	v_mfma_f32_16x16x32_bf16 v[94:97], v[142:145], v[202:205], v[94:97]
	v_mfma_f32_16x16x32_bf16 v[90:93], v[152:155], v[202:205], v[90:93]
	v_mfma_f32_16x16x32_bf16 v[86:89], v[142:145], v[210:213], v[86:89]
	v_mfma_f32_16x16x32_bf16 v[82:85], v[152:155], v[210:213], v[82:85]
	v_mfma_f32_16x16x32_bf16 v[122:125], v[148:151], v[190:193], v[122:125]
	v_mfma_f32_16x16x32_bf16 v[126:129], v[156:159], v[190:193], v[126:129]
	v_mfma_f32_16x16x32_bf16 v[114:117], v[148:151], v[198:201], v[114:117]
	v_mfma_f32_16x16x32_bf16 v[118:121], v[156:159], v[198:201], v[118:121]
	v_mfma_f32_16x16x32_bf16 v[94:97], v[148:151], v[206:209], v[94:97]
	v_mfma_f32_16x16x32_bf16 v[90:93], v[156:159], v[206:209], v[90:93]
	v_mfma_f32_16x16x32_bf16 v[86:89], v[148:151], v[214:217], v[86:89]
	v_mfma_f32_16x16x32_bf16 v[82:85], v[156:159], v[214:217], v[82:85]
	s_setprio 0
	s_setprio 1
	v_mfma_f32_16x16x32_bf16 v[110:113], v[160:163], v[186:189], v[110:113]
	v_mfma_f32_16x16x32_bf16 v[106:109], v[178:181], v[186:189], v[106:109]
	v_mfma_f32_16x16x32_bf16 v[102:105], v[160:163], v[194:197], v[102:105]
	v_mfma_f32_16x16x32_bf16 v[98:101], v[178:181], v[194:197], v[98:101]
	v_mfma_f32_16x16x32_bf16 v[78:81], v[160:163], v[202:205], v[78:81]
	v_mfma_f32_16x16x32_bf16 v[74:77], v[178:181], v[202:205], v[74:77]
	v_mfma_f32_16x16x32_bf16 v[70:73], v[160:163], v[210:213], v[70:73]
	v_mfma_f32_16x16x32_bf16 v[66:69], v[178:181], v[210:213], v[66:69]
	v_mfma_f32_16x16x32_bf16 v[110:113], v[172:175], v[190:193], v[110:113]
	v_mfma_f32_16x16x32_bf16 v[106:109], v[182:185], v[190:193], v[106:109]
	v_mfma_f32_16x16x32_bf16 v[102:105], v[172:175], v[198:201], v[102:105]
	v_mfma_f32_16x16x32_bf16 v[98:101], v[182:185], v[198:201], v[98:101]
	v_mfma_f32_16x16x32_bf16 v[78:81], v[172:175], v[206:209], v[78:81]
	v_mfma_f32_16x16x32_bf16 v[74:77], v[182:185], v[206:209], v[74:77]
	v_mfma_f32_16x16x32_bf16 v[70:73], v[172:175], v[214:217], v[70:73]
	v_mfma_f32_16x16x32_bf16 v[66:69], v[182:185], v[214:217], v[66:69]
	s_setprio 0
	s_barrier
	s_add_i32 s72, s63, s53
	v_lshl_add_u64 v[218:219], s[42:43], 0, v[132:133]
	s_mov_b32 m0, s72
	ds_read_b128 v[186:189], v168 offset:16384
	ds_read_b128 v[190:193], v168 offset:17408
	ds_read_b128 v[194:197], v168 offset:18432
	ds_read_b128 v[198:201], v168 offset:19456
	ds_read_b128 v[202:205], v168 offset:20480
	ds_read_b128 v[206:209], v168 offset:21504
	ds_read_b128 v[210:213], v168 offset:22528
	ds_read_b128 v[214:217], v168 offset:23552
	global_load_lds_dwordx4 v[218:219], off
	s_add_i32 m0, s72, 0x2000
	s_add_u32 s72, s42, 0x80000
	v_lshl_add_u64 v[220:221], s[42:43], 0, v[130:131]
	s_addc_u32 s73, s43, 0
	s_add_i32 s83, s64, s53
	global_load_lds_dwordx4 v[220:221], off
	s_mov_b32 m0, s83
	v_lshl_add_u64 v[224:225], s[44:45], 0, v[130:131]
	global_load_lds_dwordx4 v132, s[72:73]
	s_add_i32 m0, s83, 0x2000
	s_nop 0
	global_load_lds_dwordx4 v130, s[72:73]
	v_lshl_add_u64 v[222:223], s[44:45], 0, v[132:133]
	s_mov_b32 m0, s39
	s_nop 0
	global_load_lds_dwordx4 v[222:223], off
	s_mov_b32 m0, s55
	s_nop 0
	global_load_lds_dwordx4 v[224:225], off
	s_waitcnt vmcnt(8)
	s_waitcnt lgkmcnt(0)
	s_barrier
	s_setprio 1
	s_waitcnt lgkmcnt(0)
	v_mfma_f32_16x16x32_bf16 v[62:65], v[142:145], v[186:189], v[62:65]
	v_mfma_f32_16x16x32_bf16 v[58:61], v[152:155], v[186:189], v[58:61]
	v_mfma_f32_16x16x32_bf16 v[54:57], v[142:145], v[194:197], v[54:57]
	v_mfma_f32_16x16x32_bf16 v[50:53], v[152:155], v[194:197], v[50:53]
	v_mfma_f32_16x16x32_bf16 v[30:33], v[142:145], v[202:205], v[30:33]
	v_mfma_f32_16x16x32_bf16 v[26:29], v[152:155], v[202:205], v[26:29]
	v_mfma_f32_16x16x32_bf16 v[22:25], v[142:145], v[210:213], v[22:25]
	v_mfma_f32_16x16x32_bf16 v[18:21], v[152:155], v[210:213], v[18:21]
	v_mfma_f32_16x16x32_bf16 v[62:65], v[148:151], v[190:193], v[62:65]
	v_mfma_f32_16x16x32_bf16 v[58:61], v[156:159], v[190:193], v[58:61]
	v_mfma_f32_16x16x32_bf16 v[54:57], v[148:151], v[198:201], v[54:57]
	v_mfma_f32_16x16x32_bf16 v[50:53], v[156:159], v[198:201], v[50:53]
	v_mfma_f32_16x16x32_bf16 v[30:33], v[148:151], v[206:209], v[30:33]
	v_mfma_f32_16x16x32_bf16 v[26:29], v[156:159], v[206:209], v[26:29]
	v_mfma_f32_16x16x32_bf16 v[22:25], v[148:151], v[214:217], v[22:25]
	v_mfma_f32_16x16x32_bf16 v[18:21], v[156:159], v[214:217], v[18:21]
	s_setprio 0
	s_setprio 1
	v_mfma_f32_16x16x32_bf16 v[46:49], v[160:163], v[186:189], v[46:49]
	v_mfma_f32_16x16x32_bf16 v[42:45], v[178:181], v[186:189], v[42:45]
	v_mfma_f32_16x16x32_bf16 v[38:41], v[160:163], v[194:197], v[38:41]
	v_mfma_f32_16x16x32_bf16 v[34:37], v[178:181], v[194:197], v[34:37]
	v_mfma_f32_16x16x32_bf16 v[14:17], v[160:163], v[202:205], v[14:17]
	v_mfma_f32_16x16x32_bf16 v[10:13], v[178:181], v[202:205], v[10:13]
	v_mfma_f32_16x16x32_bf16 v[6:9], v[160:163], v[210:213], v[6:9]
	v_mfma_f32_16x16x32_bf16 v[2:5], v[178:181], v[210:213], v[2:5]
	v_mfma_f32_16x16x32_bf16 v[46:49], v[172:175], v[190:193], v[46:49]
	v_mfma_f32_16x16x32_bf16 v[42:45], v[182:185], v[190:193], v[42:45]
	v_mfma_f32_16x16x32_bf16 v[38:41], v[172:175], v[198:201], v[38:41]
	v_mfma_f32_16x16x32_bf16 v[34:37], v[182:185], v[198:201], v[34:37]
	v_mfma_f32_16x16x32_bf16 v[14:17], v[172:175], v[206:209], v[14:17]
	v_mfma_f32_16x16x32_bf16 v[10:13], v[182:185], v[206:209], v[10:13]
	v_mfma_f32_16x16x32_bf16 v[6:9], v[172:175], v[214:217], v[6:9]
	v_mfma_f32_16x16x32_bf16 v[2:5], v[182:185], v[214:217], v[2:5]
	s_setprio 0
	s_barrier
	s_add_i32 s72, 0, 0x18000
	s_add_i32 s73, 0, 0x1c000
	v_add_u32_e32 v156, s72, v164
	v_add_u32_e32 v171, s73, v164
	ds_read_b128 v[142:145], v156
	ds_read_b128 v[148:151], v156 offset:1024
	ds_read_b128 v[152:155], v156 offset:2048
	ds_read_b128 v[156:159], v156 offset:3072
	ds_read_b128 v[160:163], v171
	ds_read_b128 v[172:175], v171 offset:1024
	ds_read_b128 v[178:181], v171 offset:2048
	ds_read_b128 v[182:185], v171 offset:3072
	s_add_u32 s44, s44, 0x80000
	s_addc_u32 s45, s45, 0
	s_mov_b32 m0, s56
	ds_read_b128 v[186:189], v168 offset:32768
	ds_read_b128 v[190:193], v168 offset:33792
	ds_read_b128 v[194:197], v168 offset:34816
	ds_read_b128 v[198:201], v168 offset:35840
	ds_read_b128 v[202:205], v168 offset:36864
	ds_read_b128 v[206:209], v168 offset:37888
	ds_read_b128 v[210:213], v168 offset:38912
	ds_read_b128 v[214:217], v168 offset:39936
	global_load_lds_dwordx4 v132, s[44:45]
	s_mov_b32 m0, s57
	s_nop 0
	global_load_lds_dwordx4 v130, s[44:45]
	s_waitcnt vmcnt(8)
	s_waitcnt lgkmcnt(0)
	s_barrier
	s_setprio 1
	s_waitcnt lgkmcnt(0)
	v_mfma_f32_16x16x32_bf16 v[122:125], v[142:145], v[186:189], v[122:125]
	v_mfma_f32_16x16x32_bf16 v[126:129], v[152:155], v[186:189], v[126:129]
	v_mfma_f32_16x16x32_bf16 v[114:117], v[142:145], v[194:197], v[114:117]
	v_mfma_f32_16x16x32_bf16 v[118:121], v[152:155], v[194:197], v[118:121]
	v_mfma_f32_16x16x32_bf16 v[94:97], v[142:145], v[202:205], v[94:97]
	v_mfma_f32_16x16x32_bf16 v[90:93], v[152:155], v[202:205], v[90:93]
	v_mfma_f32_16x16x32_bf16 v[86:89], v[142:145], v[210:213], v[86:89]
	v_mfma_f32_16x16x32_bf16 v[82:85], v[152:155], v[210:213], v[82:85]
	v_mfma_f32_16x16x32_bf16 v[122:125], v[148:151], v[190:193], v[122:125]
	v_mfma_f32_16x16x32_bf16 v[126:129], v[156:159], v[190:193], v[126:129]
	v_mfma_f32_16x16x32_bf16 v[114:117], v[148:151], v[198:201], v[114:117]
	v_mfma_f32_16x16x32_bf16 v[118:121], v[156:159], v[198:201], v[118:121]
	v_mfma_f32_16x16x32_bf16 v[94:97], v[148:151], v[206:209], v[94:97]
	v_mfma_f32_16x16x32_bf16 v[90:93], v[156:159], v[206:209], v[90:93]
	v_mfma_f32_16x16x32_bf16 v[86:89], v[148:151], v[214:217], v[86:89]
	v_mfma_f32_16x16x32_bf16 v[82:85], v[156:159], v[214:217], v[82:85]
	s_setprio 0
	s_setprio 1
	v_mfma_f32_16x16x32_bf16 v[110:113], v[160:163], v[186:189], v[110:113]
	v_mfma_f32_16x16x32_bf16 v[106:109], v[178:181], v[186:189], v[106:109]
	v_mfma_f32_16x16x32_bf16 v[102:105], v[160:163], v[194:197], v[102:105]
	v_mfma_f32_16x16x32_bf16 v[98:101], v[178:181], v[194:197], v[98:101]
	v_mfma_f32_16x16x32_bf16 v[78:81], v[160:163], v[202:205], v[78:81]
	v_mfma_f32_16x16x32_bf16 v[74:77], v[178:181], v[202:205], v[74:77]
	v_mfma_f32_16x16x32_bf16 v[70:73], v[160:163], v[210:213], v[70:73]
	v_mfma_f32_16x16x32_bf16 v[66:69], v[178:181], v[210:213], v[66:69]
	v_mfma_f32_16x16x32_bf16 v[110:113], v[172:175], v[190:193], v[110:113]
	v_mfma_f32_16x16x32_bf16 v[106:109], v[182:185], v[190:193], v[106:109]
	v_mfma_f32_16x16x32_bf16 v[102:105], v[172:175], v[198:201], v[102:105]
	v_mfma_f32_16x16x32_bf16 v[98:101], v[182:185], v[198:201], v[98:101]
	v_mfma_f32_16x16x32_bf16 v[78:81], v[172:175], v[206:209], v[78:81]
	v_mfma_f32_16x16x32_bf16 v[74:77], v[182:185], v[206:209], v[74:77]
	v_mfma_f32_16x16x32_bf16 v[70:73], v[172:175], v[214:217], v[70:73]
	v_mfma_f32_16x16x32_bf16 v[66:69], v[182:185], v[214:217], v[66:69]
	s_setprio 0
	s_barrier
	s_add_i32 s44, s72, s53
	v_lshl_add_u64 v[218:219], v[218:219], 0, s[8:9]
	s_mov_b32 m0, s44
	ds_read_b128 v[186:189], v168 offset:49152
	ds_read_b128 v[190:193], v168 offset:50176
	ds_read_b128 v[194:197], v168 offset:51200
	ds_read_b128 v[198:201], v168 offset:52224
	ds_read_b128 v[202:205], v168 offset:53248
	ds_read_b128 v[206:209], v168 offset:54272
	ds_read_b128 v[210:213], v168 offset:55296
	ds_read_b128 v[214:217], v168 offset:56320
	global_load_lds_dwordx4 v[218:219], off
	s_add_i32 m0, s44, 0x2000
	s_add_u32 s42, s42, 0x80080
	v_lshl_add_u64 v[218:219], v[220:221], 0, s[8:9]
	s_addc_u32 s43, s43, 0
	s_add_i32 s44, s73, s53
	global_load_lds_dwordx4 v[218:219], off
	s_mov_b32 m0, s44
	s_nop 0
	global_load_lds_dwordx4 v132, s[42:43]
	s_add_i32 m0, s44, 0x2000
	s_nop 0
	global_load_lds_dwordx4 v130, s[42:43]
	v_lshl_add_u64 v[218:219], v[222:223], 0, s[8:9]
	s_mov_b32 m0, s61
	s_nop 0
	global_load_lds_dwordx4 v[218:219], off
	v_lshl_add_u64 v[218:219], v[224:225], 0, s[8:9]
	s_mov_b32 m0, s62
	s_nop 0
	global_load_lds_dwordx4 v[218:219], off
	s_waitcnt vmcnt(8)
	s_waitcnt lgkmcnt(0)
	s_barrier
	s_setprio 1
	s_waitcnt lgkmcnt(0)
	v_mfma_f32_16x16x32_bf16 v[62:65], v[142:145], v[186:189], v[62:65]
	v_mfma_f32_16x16x32_bf16 v[58:61], v[152:155], v[186:189], v[58:61]
	v_mfma_f32_16x16x32_bf16 v[54:57], v[142:145], v[194:197], v[54:57]
	v_mfma_f32_16x16x32_bf16 v[50:53], v[152:155], v[194:197], v[50:53]
	v_mfma_f32_16x16x32_bf16 v[30:33], v[142:145], v[202:205], v[30:33]
	v_mfma_f32_16x16x32_bf16 v[26:29], v[152:155], v[202:205], v[26:29]
	v_mfma_f32_16x16x32_bf16 v[22:25], v[142:145], v[210:213], v[22:25]
	v_mfma_f32_16x16x32_bf16 v[18:21], v[152:155], v[210:213], v[18:21]
	v_mfma_f32_16x16x32_bf16 v[62:65], v[148:151], v[190:193], v[62:65]
	v_mfma_f32_16x16x32_bf16 v[58:61], v[156:159], v[190:193], v[58:61]
	v_mfma_f32_16x16x32_bf16 v[54:57], v[148:151], v[198:201], v[54:57]
	v_mfma_f32_16x16x32_bf16 v[50:53], v[156:159], v[198:201], v[50:53]
	v_mfma_f32_16x16x32_bf16 v[30:33], v[148:151], v[206:209], v[30:33]
	v_mfma_f32_16x16x32_bf16 v[26:29], v[156:159], v[206:209], v[26:29]
	v_mfma_f32_16x16x32_bf16 v[22:25], v[148:151], v[214:217], v[22:25]
	v_mfma_f32_16x16x32_bf16 v[18:21], v[156:159], v[214:217], v[18:21]
	s_setprio 0
	s_setprio 1
	v_mfma_f32_16x16x32_bf16 v[46:49], v[160:163], v[186:189], v[46:49]
	v_mfma_f32_16x16x32_bf16 v[42:45], v[178:181], v[186:189], v[42:45]
	v_mfma_f32_16x16x32_bf16 v[38:41], v[160:163], v[194:197], v[38:41]
	v_mfma_f32_16x16x32_bf16 v[34:37], v[178:181], v[194:197], v[34:37]
	v_mfma_f32_16x16x32_bf16 v[14:17], v[160:163], v[202:205], v[14:17]
	v_mfma_f32_16x16x32_bf16 v[10:13], v[178:181], v[202:205], v[10:13]
	v_mfma_f32_16x16x32_bf16 v[6:9], v[160:163], v[210:213], v[6:9]
	v_mfma_f32_16x16x32_bf16 v[2:5], v[178:181], v[210:213], v[2:5]
	v_mfma_f32_16x16x32_bf16 v[46:49], v[172:175], v[190:193], v[46:49]
	v_mfma_f32_16x16x32_bf16 v[42:45], v[182:185], v[190:193], v[42:45]
	v_mfma_f32_16x16x32_bf16 v[38:41], v[172:175], v[198:201], v[38:41]
	v_mfma_f32_16x16x32_bf16 v[34:37], v[182:185], v[198:201], v[34:37]
	v_mfma_f32_16x16x32_bf16 v[14:17], v[172:175], v[206:209], v[14:17]
	v_mfma_f32_16x16x32_bf16 v[10:13], v[182:185], v[206:209], v[10:13]
	v_mfma_f32_16x16x32_bf16 v[6:9], v[172:175], v[214:217], v[6:9]
	v_mfma_f32_16x16x32_bf16 v[2:5], v[182:185], v[214:217], v[2:5]
	s_setprio 0
	s_barrier
	s_add_i32 s82, s82, 2
	s_add_u32 s40, s40, 0x100
	s_addc_u32 s41, s41, 0
	s_add_u32 s75, s75, 0x100
	s_addc_u32 s81, s81, 0
	s_cmp_gt_u32 s82, 29
	s_cbranch_scc0 .LBB0_890
	s_and_b64 vcc, exec, s[16:17]
	s_cbranch_vccz .LBB0_893
	s_barrier

.LBB0_1043:
	ds_read_b128 v[154:157], v150
	ds_read_b128 v[158:161], v150 offset:1024
	ds_read_b128 v[162:165], v150 offset:2048
	ds_read_b128 v[166:169], v150 offset:3072
	ds_read_b128 v[170:173], v151
	ds_read_b128 v[178:181], v151 offset:1024
	ds_read_b128 v[182:185], v151 offset:2048
	ds_read_b128 v[186:189], v151 offset:3072
	s_add_u32 s38, s36, 0xfff80080
	s_addc_u32 s39, s37, -1
	s_cmp_eq_u32 s63, 28
	s_cselect_b32 s41, s13, s39
	s_cselect_b32 s40, s19, s38
	s_cselect_b32 s39, s17, s62
	s_cselect_b32 s38, s60, s61
	s_add_i32 m0, s25, 0xc000
	ds_read_b128 v[190:193], v152
	ds_read_b128 v[194:197], v152 offset:1024
	ds_read_b128 v[198:201], v152 offset:2048
	ds_read_b128 v[202:205], v152 offset:3072
	ds_read_b128 v[206:209], v152 offset:4096
	ds_read_b128 v[210:213], v152 offset:5120
	ds_read_b128 v[214:217], v152 offset:6144
	ds_read_b128 v[218:221], v152 offset:7168
	global_load_lds_dwordx4 v138, s[36:37]
	s_add_i32 m0, s25, 0xe000
	s_nop 0
	global_load_lds_dwordx4 v140, s[36:37]
	s_waitcnt vmcnt(8)
	s_waitcnt lgkmcnt(0)
	s_barrier
	s_setprio 1
	s_waitcnt lgkmcnt(0)
	v_mfma_f32_16x16x32_bf16 v[126:129], v[154:157], v[190:193], v[126:129]
	v_mfma_f32_16x16x32_bf16 v[122:125], v[162:165], v[190:193], v[122:125]
	v_mfma_f32_16x16x32_bf16 v[110:113], v[154:157], v[198:201], v[110:113]
	v_mfma_f32_16x16x32_bf16 v[106:109], v[162:165], v[198:201], v[106:109]
	v_mfma_f32_16x16x32_bf16 v[94:97], v[154:157], v[206:209], v[94:97]
	v_mfma_f32_16x16x32_bf16 v[90:93], v[162:165], v[206:209], v[90:93]
	v_mfma_f32_16x16x32_bf16 v[78:81], v[154:157], v[214:217], v[78:81]
	v_mfma_f32_16x16x32_bf16 v[74:77], v[162:165], v[214:217], v[74:77]
	v_mfma_f32_16x16x32_bf16 v[126:129], v[158:161], v[194:197], v[126:129]
	v_mfma_f32_16x16x32_bf16 v[122:125], v[166:169], v[194:197], v[122:125]
	v_mfma_f32_16x16x32_bf16 v[110:113], v[158:161], v[202:205], v[110:113]
	v_mfma_f32_16x16x32_bf16 v[106:109], v[166:169], v[202:205], v[106:109]
	v_mfma_f32_16x16x32_bf16 v[94:97], v[158:161], v[210:213], v[94:97]
	v_mfma_f32_16x16x32_bf16 v[90:93], v[166:169], v[210:213], v[90:93]
	v_mfma_f32_16x16x32_bf16 v[78:81], v[158:161], v[218:221], v[78:81]
	v_mfma_f32_16x16x32_bf16 v[74:77], v[166:169], v[218:221], v[74:77]
	s_setprio 0
	s_setprio 1
	v_mfma_f32_16x16x32_bf16 v[118:121], v[170:173], v[190:193], v[118:121]
	v_mfma_f32_16x16x32_bf16 v[114:117], v[182:185], v[190:193], v[114:117]
	v_mfma_f32_16x16x32_bf16 v[102:105], v[170:173], v[198:201], v[102:105]
	v_mfma_f32_16x16x32_bf16 v[98:101], v[182:185], v[198:201], v[98:101]
	v_mfma_f32_16x16x32_bf16 v[86:89], v[170:173], v[206:209], v[86:89]
	v_mfma_f32_16x16x32_bf16 v[82:85], v[182:185], v[206:209], v[82:85]
	v_mfma_f32_16x16x32_bf16 v[70:73], v[170:173], v[214:217], v[70:73]
	v_mfma_f32_16x16x32_bf16 v[66:69], v[182:185], v[214:217], v[66:69]
	v_mfma_f32_16x16x32_bf16 v[118:121], v[178:181], v[194:197], v[118:121]
	v_mfma_f32_16x16x32_bf16 v[114:117], v[186:189], v[194:197], v[114:117]
	v_mfma_f32_16x16x32_bf16 v[102:105], v[178:181], v[202:205], v[102:105]
	v_mfma_f32_16x16x32_bf16 v[98:101], v[186:189], v[202:205], v[98:101]
	v_mfma_f32_16x16x32_bf16 v[86:89], v[178:181], v[210:213], v[86:89]
	v_mfma_f32_16x16x32_bf16 v[82:85], v[186:189], v[210:213], v[82:85]
	v_mfma_f32_16x16x32_bf16 v[70:73], v[178:181], v[218:221], v[70:73]
	v_mfma_f32_16x16x32_bf16 v[66:69], v[186:189], v[218:221], v[66:69]
	s_setprio 0
	s_barrier
	s_add_i32 s64, s57, s45
	v_lshl_add_u64 v[174:175], s[38:39], 0, v[134:135]
	s_mov_b32 m0, s64
	ds_read_b128 v[190:193], v152 offset:16384
	ds_read_b128 v[194:197], v152 offset:17408
	ds_read_b128 v[198:201], v152 offset:18432
	ds_read_b128 v[202:205], v152 offset:19456
	ds_read_b128 v[206:209], v152 offset:20480
	ds_read_b128 v[210:213], v152 offset:21504
	ds_read_b128 v[214:217], v152 offset:22528
	ds_read_b128 v[218:221], v152 offset:23552
	global_load_lds_dwordx4 v[174:175], off
	s_add_i32 m0, s64, 0x2000
	s_add_u32 s64, s38, 0x80000
	v_lshl_add_u64 v[222:223], s[38:39], 0, v[130:131]
	s_addc_u32 s65, s39, 0
	s_add_i32 s66, s58, s45
	global_load_lds_dwordx4 v[222:223], off
	s_mov_b32 m0, s66
	v_lshl_add_u64 v[226:227], s[40:41], 0, v[132:133]
	global_load_lds_dwordx4 v134, s[64:65]
	s_add_i32 m0, s66, 0x2000
	s_nop 0
	global_load_lds_dwordx4 v130, s[64:65]
	v_lshl_add_u64 v[224:225], s[40:41], 0, v[136:137]
	s_mov_b32 m0, s25
	s_nop 0
	global_load_lds_dwordx4 v[224:225], off
	s_mov_b32 m0, s50
	s_nop 0
	global_load_lds_dwordx4 v[226:227], off
	s_waitcnt vmcnt(8)
	s_waitcnt lgkmcnt(0)
	s_barrier
	s_setprio 1
	s_waitcnt lgkmcnt(0)
	v_mfma_f32_16x16x32_bf16 v[62:65], v[154:157], v[190:193], v[62:65]
	v_mfma_f32_16x16x32_bf16 v[58:61], v[162:165], v[190:193], v[58:61]
	v_mfma_f32_16x16x32_bf16 v[46:49], v[154:157], v[198:201], v[46:49]
	v_mfma_f32_16x16x32_bf16 v[42:45], v[162:165], v[198:201], v[42:45]
	v_mfma_f32_16x16x32_bf16 v[30:33], v[154:157], v[206:209], v[30:33]
	v_mfma_f32_16x16x32_bf16 v[26:29], v[162:165], v[206:209], v[26:29]
	v_mfma_f32_16x16x32_bf16 v[14:17], v[154:157], v[214:217], v[14:17]
	v_mfma_f32_16x16x32_bf16 v[10:13], v[162:165], v[214:217], v[10:13]
	v_mfma_f32_16x16x32_bf16 v[62:65], v[158:161], v[194:197], v[62:65]
	v_mfma_f32_16x16x32_bf16 v[58:61], v[166:169], v[194:197], v[58:61]
	v_mfma_f32_16x16x32_bf16 v[46:49], v[158:161], v[202:205], v[46:49]
	v_mfma_f32_16x16x32_bf16 v[42:45], v[166:169], v[202:205], v[42:45]
	v_mfma_f32_16x16x32_bf16 v[30:33], v[158:161], v[210:213], v[30:33]
	v_mfma_f32_16x16x32_bf16 v[26:29], v[166:169], v[210:213], v[26:29]
	v_mfma_f32_16x16x32_bf16 v[14:17], v[158:161], v[218:221], v[14:17]
	v_mfma_f32_16x16x32_bf16 v[10:13], v[166:169], v[218:221], v[10:13]
	s_setprio 0
	s_setprio 1
	v_mfma_f32_16x16x32_bf16 v[54:57], v[170:173], v[190:193], v[54:57]
	v_mfma_f32_16x16x32_bf16 v[50:53], v[182:185], v[190:193], v[50:53]
	v_mfma_f32_16x16x32_bf16 v[38:41], v[170:173], v[198:201], v[38:41]
	v_mfma_f32_16x16x32_bf16 v[34:37], v[182:185], v[198:201], v[34:37]
	v_mfma_f32_16x16x32_bf16 v[22:25], v[170:173], v[206:209], v[22:25]
	v_mfma_f32_16x16x32_bf16 v[18:21], v[182:185], v[206:209], v[18:21]
	v_mfma_f32_16x16x32_bf16 v[6:9], v[170:173], v[214:217], v[6:9]
	v_mfma_f32_16x16x32_bf16 v[2:5], v[182:185], v[214:217], v[2:5]
	v_mfma_f32_16x16x32_bf16 v[54:57], v[178:181], v[194:197], v[54:57]
	v_mfma_f32_16x16x32_bf16 v[50:53], v[186:189], v[194:197], v[50:53]
	v_mfma_f32_16x16x32_bf16 v[38:41], v[178:181], v[202:205], v[38:41]
	v_mfma_f32_16x16x32_bf16 v[34:37], v[186:189], v[202:205], v[34:37]
	v_mfma_f32_16x16x32_bf16 v[22:25], v[178:181], v[210:213], v[22:25]
	v_mfma_f32_16x16x32_bf16 v[18:21], v[186:189], v[210:213], v[18:21]
	v_mfma_f32_16x16x32_bf16 v[6:9], v[178:181], v[218:221], v[6:9]
	v_mfma_f32_16x16x32_bf16 v[2:5], v[186:189], v[218:221], v[2:5]
	s_setprio 0
	s_barrier
	s_add_i32 s64, 0, 0x18000
	v_add_u32_e32 v153, s64, v148
	s_add_i32 s65, 0, 0x1c000
	ds_read_b128 v[154:157], v153
	ds_read_b128 v[158:161], v153 offset:1024
	ds_read_b128 v[162:165], v153 offset:2048
	ds_read_b128 v[166:169], v153 offset:3072
	v_add_u32_e32 v153, s65, v148
	ds_read_b128 v[170:173], v153
	ds_read_b128 v[178:181], v153 offset:1024
	ds_read_b128 v[182:185], v153 offset:2048
	ds_read_b128 v[186:189], v153 offset:3072
	s_add_u32 s40, s40, 0x80000
	s_addc_u32 s41, s41, 0
	s_mov_b32 m0, s51
	ds_read_b128 v[190:193], v152 offset:32768
	ds_read_b128 v[194:197], v152 offset:33792
	ds_read_b128 v[198:201], v152 offset:34816
	ds_read_b128 v[202:205], v152 offset:35840
	ds_read_b128 v[206:209], v152 offset:36864
	ds_read_b128 v[210:213], v152 offset:37888
	ds_read_b128 v[214:217], v152 offset:38912
	ds_read_b128 v[218:221], v152 offset:39936
	global_load_lds_dwordx4 v136, s[40:41]
	s_mov_b32 m0, s52
	s_nop 0
	global_load_lds_dwordx4 v132, s[40:41]
	s_waitcnt vmcnt(8)
	s_waitcnt lgkmcnt(0)
	s_barrier
	s_setprio 1
	s_waitcnt lgkmcnt(0)
	v_mfma_f32_16x16x32_bf16 v[126:129], v[154:157], v[190:193], v[126:129]
	v_mfma_f32_16x16x32_bf16 v[122:125], v[162:165], v[190:193], v[122:125]
	v_mfma_f32_16x16x32_bf16 v[110:113], v[154:157], v[198:201], v[110:113]
	v_mfma_f32_16x16x32_bf16 v[106:109], v[162:165], v[198:201], v[106:109]
	v_mfma_f32_16x16x32_bf16 v[94:97], v[154:157], v[206:209], v[94:97]
	v_mfma_f32_16x16x32_bf16 v[90:93], v[162:165], v[206:209], v[90:93]
	v_mfma_f32_16x16x32_bf16 v[78:81], v[154:157], v[214:217], v[78:81]
	v_mfma_f32_16x16x32_bf16 v[74:77], v[162:165], v[214:217], v[74:77]
	v_mfma_f32_16x16x32_bf16 v[126:129], v[158:161], v[194:197], v[126:129]
	v_mfma_f32_16x16x32_bf16 v[122:125], v[166:169], v[194:197], v[122:125]
	v_mfma_f32_16x16x32_bf16 v[110:113], v[158:161], v[202:205], v[110:113]
	v_mfma_f32_16x16x32_bf16 v[106:109], v[166:169], v[202:205], v[106:109]
	v_mfma_f32_16x16x32_bf16 v[94:97], v[158:161], v[210:213], v[94:97]
	v_mfma_f32_16x16x32_bf16 v[90:93], v[166:169], v[210:213], v[90:93]
	v_mfma_f32_16x16x32_bf16 v[78:81], v[158:161], v[218:221], v[78:81]
	v_mfma_f32_16x16x32_bf16 v[74:77], v[166:169], v[218:221], v[74:77]
	s_setprio 0
	s_setprio 1
	v_mfma_f32_16x16x32_bf16 v[118:121], v[170:173], v[190:193], v[118:121]
	v_mfma_f32_16x16x32_bf16 v[114:117], v[182:185], v[190:193], v[114:117]
	v_mfma_f32_16x16x32_bf16 v[102:105], v[170:173], v[198:201], v[102:105]
	v_mfma_f32_16x16x32_bf16 v[98:101], v[182:185], v[198:201], v[98:101]
	v_mfma_f32_16x16x32_bf16 v[86:89], v[170:173], v[206:209], v[86:89]
	v_mfma_f32_16x16x32_bf16 v[82:85], v[182:185], v[206:209], v[82:85]
	v_mfma_f32_16x16x32_bf16 v[70:73], v[170:173], v[214:217], v[70:73]
	v_mfma_f32_16x16x32_bf16 v[66:69], v[182:185], v[214:217], v[66:69]
	v_mfma_f32_16x16x32_bf16 v[118:121], v[178:181], v[194:197], v[118:121]
	v_mfma_f32_16x16x32_bf16 v[114:117], v[186:189], v[194:197], v[114:117]
	v_mfma_f32_16x16x32_bf16 v[102:105], v[178:181], v[202:205], v[102:105]
	v_mfma_f32_16x16x32_bf16 v[98:101], v[186:189], v[202:205], v[98:101]
	v_mfma_f32_16x16x32_bf16 v[86:89], v[178:181], v[210:213], v[86:89]
	v_mfma_f32_16x16x32_bf16 v[82:85], v[186:189], v[210:213], v[82:85]
	v_mfma_f32_16x16x32_bf16 v[70:73], v[178:181], v[218:221], v[70:73]
	v_mfma_f32_16x16x32_bf16 v[66:69], v[186:189], v[218:221], v[66:69]
	s_setprio 0
	s_barrier
	s_add_i32 s40, s64, s45
	v_lshl_add_u64 v[174:175], v[174:175], 0, s[8:9]
	s_mov_b32 m0, s40
	ds_read_b128 v[190:193], v152 offset:49152
	ds_read_b128 v[194:197], v152 offset:50176
	ds_read_b128 v[198:201], v152 offset:51200
	ds_read_b128 v[202:205], v152 offset:52224
	ds_read_b128 v[206:209], v152 offset:53248
	ds_read_b128 v[210:213], v152 offset:54272
	ds_read_b128 v[214:217], v152 offset:55296
	ds_read_b128 v[218:221], v152 offset:56320
	global_load_lds_dwordx4 v[174:175], off
	s_add_i32 m0, s40, 0x2000
	s_add_u32 s38, s38, 0x80080
	v_lshl_add_u64 v[174:175], v[222:223], 0, s[8:9]
	s_addc_u32 s39, s39, 0
	s_add_i32 s40, s65, s45
	global_load_lds_dwordx4 v[174:175], off
	s_mov_b32 m0, s40
	s_nop 0
	global_load_lds_dwordx4 v134, s[38:39]
	s_add_i32 m0, s40, 0x2000
	s_nop 0
	global_load_lds_dwordx4 v130, s[38:39]
	v_lshl_add_u64 v[174:175], v[224:225], 0, s[8:9]
	s_mov_b32 m0, s55
	s_nop 0
	global_load_lds_dwordx4 v[174:175], off
	v_lshl_add_u64 v[174:175], v[226:227], 0, s[8:9]
	s_mov_b32 m0, s56
	s_nop 0
	global_load_lds_dwordx4 v[174:175], off
	s_waitcnt vmcnt(8)
	s_waitcnt lgkmcnt(0)
	s_barrier
	s_setprio 1
	s_waitcnt lgkmcnt(0)
	v_mfma_f32_16x16x32_bf16 v[62:65], v[154:157], v[190:193], v[62:65]
	v_mfma_f32_16x16x32_bf16 v[58:61], v[162:165], v[190:193], v[58:61]
	v_mfma_f32_16x16x32_bf16 v[46:49], v[154:157], v[198:201], v[46:49]
	v_mfma_f32_16x16x32_bf16 v[42:45], v[162:165], v[198:201], v[42:45]
	v_mfma_f32_16x16x32_bf16 v[30:33], v[154:157], v[206:209], v[30:33]
	v_mfma_f32_16x16x32_bf16 v[26:29], v[162:165], v[206:209], v[26:29]
	v_mfma_f32_16x16x32_bf16 v[14:17], v[154:157], v[214:217], v[14:17]
	v_mfma_f32_16x16x32_bf16 v[10:13], v[162:165], v[214:217], v[10:13]
	v_mfma_f32_16x16x32_bf16 v[62:65], v[158:161], v[194:197], v[62:65]
	v_mfma_f32_16x16x32_bf16 v[58:61], v[166:169], v[194:197], v[58:61]
	v_mfma_f32_16x16x32_bf16 v[46:49], v[158:161], v[202:205], v[46:49]
	v_mfma_f32_16x16x32_bf16 v[42:45], v[166:169], v[202:205], v[42:45]
	v_mfma_f32_16x16x32_bf16 v[30:33], v[158:161], v[210:213], v[30:33]
	v_mfma_f32_16x16x32_bf16 v[26:29], v[166:169], v[210:213], v[26:29]
	v_mfma_f32_16x16x32_bf16 v[14:17], v[158:161], v[218:221], v[14:17]
	v_mfma_f32_16x16x32_bf16 v[10:13], v[166:169], v[218:221], v[10:13]
	s_setprio 0
	s_setprio 1
	v_mfma_f32_16x16x32_bf16 v[54:57], v[170:173], v[190:193], v[54:57]
	v_mfma_f32_16x16x32_bf16 v[50:53], v[182:185], v[190:193], v[50:53]
	v_mfma_f32_16x16x32_bf16 v[38:41], v[170:173], v[198:201], v[38:41]
	v_mfma_f32_16x16x32_bf16 v[34:37], v[182:185], v[198:201], v[34:37]
	v_mfma_f32_16x16x32_bf16 v[22:25], v[170:173], v[206:209], v[22:25]
	v_mfma_f32_16x16x32_bf16 v[18:21], v[182:185], v[206:209], v[18:21]
	v_mfma_f32_16x16x32_bf16 v[6:9], v[170:173], v[214:217], v[6:9]
	v_mfma_f32_16x16x32_bf16 v[2:5], v[182:185], v[214:217], v[2:5]
	v_mfma_f32_16x16x32_bf16 v[54:57], v[178:181], v[194:197], v[54:57]
	v_mfma_f32_16x16x32_bf16 v[50:53], v[186:189], v[194:197], v[50:53]
	v_mfma_f32_16x16x32_bf16 v[38:41], v[178:181], v[202:205], v[38:41]
	v_mfma_f32_16x16x32_bf16 v[34:37], v[186:189], v[202:205], v[34:37]
	v_mfma_f32_16x16x32_bf16 v[22:25], v[178:181], v[210:213], v[22:25]
	v_mfma_f32_16x16x32_bf16 v[18:21], v[186:189], v[210:213], v[18:21]
	v_mfma_f32_16x16x32_bf16 v[6:9], v[178:181], v[218:221], v[6:9]
	v_mfma_f32_16x16x32_bf16 v[2:5], v[186:189], v[218:221], v[2:5]
	s_setprio 0
	s_barrier
	s_add_i32 s63, s63, 2
	s_add_u32 s36, s36, 0x100
	s_addc_u32 s37, s37, 0
	s_add_u32 s61, s61, 0x100
	s_addc_u32 s62, s62, 0
	s_cmp_gt_u32 s63, 29
	s_cbranch_scc0 .LBB0_1043
	s_and_b64 vcc, exec, s[10:11]
	s_cbranch_vccz .LBB0_1046
	s_barrier

.LBB0_1138:
	ds_read_b128 v[142:145], v166
	ds_read_b128 v[148:151], v166 offset:1024
	ds_read_b128 v[152:155], v166 offset:2048
	ds_read_b128 v[156:159], v166 offset:3072
	ds_read_b128 v[160:163], v167
	ds_read_b128 v[172:175], v167 offset:1024
	ds_read_b128 v[178:181], v167 offset:2048
	ds_read_b128 v[182:185], v167 offset:3072
	s_add_u32 s24, s22, 0x100
	s_addc_u32 s25, s23, 0
	s_cmpk_eq_i32 s74, 0x54
	s_cselect_b32 s39, s5, s25
	s_cselect_b32 s38, s4, s24
	s_cselect_b32 s37, s21, s69
	s_cselect_b32 s36, s20, s67
	v_lshl_add_u64 v[218:219], s[22:23], 0, v[134:135]
	s_add_i32 m0, s45, 0xc000
	ds_read_b128 v[186:189], v168
	ds_read_b128 v[190:193], v168 offset:1024
	ds_read_b128 v[194:197], v168 offset:2048
	ds_read_b128 v[198:201], v168 offset:3072
	ds_read_b128 v[202:205], v168 offset:4096
	ds_read_b128 v[206:209], v168 offset:5120
	ds_read_b128 v[210:213], v168 offset:6144
	ds_read_b128 v[214:217], v168 offset:7168
	global_load_lds_dwordx4 v[218:219], off
	v_lshl_add_u64 v[218:219], s[22:23], 0, v[136:137]
	s_add_i32 m0, s45, 0xe000
	s_nop 0
	global_load_lds_dwordx4 v[218:219], off
	s_waitcnt vmcnt(8)
	s_waitcnt lgkmcnt(0)
	s_barrier
	s_setprio 1
	s_waitcnt lgkmcnt(0)
	v_mfma_f32_16x16x32_bf16 v[122:125], v[142:145], v[186:189], v[122:125]
	v_mfma_f32_16x16x32_bf16 v[126:129], v[152:155], v[186:189], v[126:129]
	v_mfma_f32_16x16x32_bf16 v[114:117], v[142:145], v[194:197], v[114:117]
	v_mfma_f32_16x16x32_bf16 v[118:121], v[152:155], v[194:197], v[118:121]
	v_mfma_f32_16x16x32_bf16 v[94:97], v[142:145], v[202:205], v[94:97]
	v_mfma_f32_16x16x32_bf16 v[90:93], v[152:155], v[202:205], v[90:93]
	v_mfma_f32_16x16x32_bf16 v[86:89], v[142:145], v[210:213], v[86:89]
	v_mfma_f32_16x16x32_bf16 v[82:85], v[152:155], v[210:213], v[82:85]
	v_mfma_f32_16x16x32_bf16 v[122:125], v[148:151], v[190:193], v[122:125]
	v_mfma_f32_16x16x32_bf16 v[126:129], v[156:159], v[190:193], v[126:129]
	v_mfma_f32_16x16x32_bf16 v[114:117], v[148:151], v[198:201], v[114:117]
	v_mfma_f32_16x16x32_bf16 v[118:121], v[156:159], v[198:201], v[118:121]
	v_mfma_f32_16x16x32_bf16 v[94:97], v[148:151], v[206:209], v[94:97]
	v_mfma_f32_16x16x32_bf16 v[90:93], v[156:159], v[206:209], v[90:93]
	v_mfma_f32_16x16x32_bf16 v[86:89], v[148:151], v[214:217], v[86:89]
	v_mfma_f32_16x16x32_bf16 v[82:85], v[156:159], v[214:217], v[82:85]
	s_setprio 0
	s_setprio 1
	v_mfma_f32_16x16x32_bf16 v[110:113], v[160:163], v[186:189], v[110:113]
	v_mfma_f32_16x16x32_bf16 v[106:109], v[178:181], v[186:189], v[106:109]
	v_mfma_f32_16x16x32_bf16 v[102:105], v[160:163], v[194:197], v[102:105]
	v_mfma_f32_16x16x32_bf16 v[98:101], v[178:181], v[194:197], v[98:101]
	v_mfma_f32_16x16x32_bf16 v[78:81], v[160:163], v[202:205], v[78:81]
	v_mfma_f32_16x16x32_bf16 v[74:77], v[178:181], v[202:205], v[74:77]
	v_mfma_f32_16x16x32_bf16 v[70:73], v[160:163], v[210:213], v[70:73]
	v_mfma_f32_16x16x32_bf16 v[66:69], v[178:181], v[210:213], v[66:69]
	v_mfma_f32_16x16x32_bf16 v[110:113], v[172:175], v[190:193], v[110:113]
	v_mfma_f32_16x16x32_bf16 v[106:109], v[182:185], v[190:193], v[106:109]
	v_mfma_f32_16x16x32_bf16 v[102:105], v[172:175], v[198:201], v[102:105]
	v_mfma_f32_16x16x32_bf16 v[98:101], v[182:185], v[198:201], v[98:101]
	v_mfma_f32_16x16x32_bf16 v[78:81], v[172:175], v[206:209], v[78:81]
	v_mfma_f32_16x16x32_bf16 v[74:77], v[182:185], v[206:209], v[74:77]
	v_mfma_f32_16x16x32_bf16 v[70:73], v[172:175], v[214:217], v[70:73]
	v_mfma_f32_16x16x32_bf16 v[66:69], v[182:185], v[214:217], v[66:69]
	s_setprio 0
	s_barrier
	s_add_i32 s22, s46, s44
	v_lshl_add_u64 v[218:219], s[36:37], 0, v[130:131]
	s_mov_b32 m0, s22
	ds_read_b128 v[186:189], v168 offset:16384
	ds_read_b128 v[190:193], v168 offset:17408
	ds_read_b128 v[194:197], v168 offset:18432
	ds_read_b128 v[198:201], v168 offset:19456
	ds_read_b128 v[202:205], v168 offset:20480
	ds_read_b128 v[206:209], v168 offset:21504
	ds_read_b128 v[210:213], v168 offset:22528
	ds_read_b128 v[214:217], v168 offset:23552
	global_load_lds_dwordx4 v[218:219], off
	s_add_i32 m0, s22, 0x2000
	s_add_u32 s22, s36, 0x160000
	v_lshl_add_u64 v[220:221], s[36:37], 0, v[132:133]
	s_addc_u32 s23, s37, 0
	s_add_i32 s72, s47, s44
	global_load_lds_dwordx4 v[220:221], off
	s_mov_b32 m0, s72
	v_lshl_add_u64 v[224:225], s[38:39], 0, v[132:133]
	global_load_lds_dwordx4 v130, s[22:23]
	s_add_i32 m0, s72, 0x2000
	s_nop 0
	global_load_lds_dwordx4 v132, s[22:23]
	v_lshl_add_u64 v[222:223], s[38:39], 0, v[130:131]
	s_mov_b32 m0, s45
	s_nop 0
	global_load_lds_dwordx4 v[222:223], off
	s_mov_b32 m0, s48
	s_nop 0
	global_load_lds_dwordx4 v[224:225], off
	s_waitcnt vmcnt(8)
	s_waitcnt lgkmcnt(0)
	s_barrier
	s_setprio 1
	s_waitcnt lgkmcnt(0)
	v_mfma_f32_16x16x32_bf16 v[62:65], v[142:145], v[186:189], v[62:65]
	v_mfma_f32_16x16x32_bf16 v[58:61], v[152:155], v[186:189], v[58:61]
	v_mfma_f32_16x16x32_bf16 v[54:57], v[142:145], v[194:197], v[54:57]
	v_mfma_f32_16x16x32_bf16 v[50:53], v[152:155], v[194:197], v[50:53]
	v_mfma_f32_16x16x32_bf16 v[30:33], v[142:145], v[202:205], v[30:33]
	v_mfma_f32_16x16x32_bf16 v[26:29], v[152:155], v[202:205], v[26:29]
	v_mfma_f32_16x16x32_bf16 v[22:25], v[142:145], v[210:213], v[22:25]
	v_mfma_f32_16x16x32_bf16 v[18:21], v[152:155], v[210:213], v[18:21]
	v_mfma_f32_16x16x32_bf16 v[62:65], v[148:151], v[190:193], v[62:65]
	v_mfma_f32_16x16x32_bf16 v[58:61], v[156:159], v[190:193], v[58:61]
	v_mfma_f32_16x16x32_bf16 v[54:57], v[148:151], v[198:201], v[54:57]
	v_mfma_f32_16x16x32_bf16 v[50:53], v[156:159], v[198:201], v[50:53]
	v_mfma_f32_16x16x32_bf16 v[30:33], v[148:151], v[206:209], v[30:33]
	v_mfma_f32_16x16x32_bf16 v[26:29], v[156:159], v[206:209], v[26:29]
	v_mfma_f32_16x16x32_bf16 v[22:25], v[148:151], v[214:217], v[22:25]
	v_mfma_f32_16x16x32_bf16 v[18:21], v[156:159], v[214:217], v[18:21]
	s_setprio 0
	s_setprio 1
	v_mfma_f32_16x16x32_bf16 v[46:49], v[160:163], v[186:189], v[46:49]
	v_mfma_f32_16x16x32_bf16 v[42:45], v[178:181], v[186:189], v[42:45]
	v_mfma_f32_16x16x32_bf16 v[38:41], v[160:163], v[194:197], v[38:41]
	v_mfma_f32_16x16x32_bf16 v[34:37], v[178:181], v[194:197], v[34:37]
	v_mfma_f32_16x16x32_bf16 v[14:17], v[160:163], v[202:205], v[14:17]
	v_mfma_f32_16x16x32_bf16 v[10:13], v[178:181], v[202:205], v[10:13]
	v_mfma_f32_16x16x32_bf16 v[6:9], v[160:163], v[210:213], v[6:9]
	v_mfma_f32_16x16x32_bf16 v[2:5], v[178:181], v[210:213], v[2:5]
	v_mfma_f32_16x16x32_bf16 v[46:49], v[172:175], v[190:193], v[46:49]
	v_mfma_f32_16x16x32_bf16 v[42:45], v[182:185], v[190:193], v[42:45]
	v_mfma_f32_16x16x32_bf16 v[38:41], v[172:175], v[198:201], v[38:41]
	v_mfma_f32_16x16x32_bf16 v[34:37], v[182:185], v[198:201], v[34:37]
	v_mfma_f32_16x16x32_bf16 v[14:17], v[172:175], v[206:209], v[14:17]
	v_mfma_f32_16x16x32_bf16 v[10:13], v[182:185], v[206:209], v[10:13]
	v_mfma_f32_16x16x32_bf16 v[6:9], v[172:175], v[214:217], v[6:9]
	v_mfma_f32_16x16x32_bf16 v[2:5], v[182:185], v[214:217], v[2:5]
	s_setprio 0
	s_barrier
	s_add_i32 s72, 0, 0x18000
	s_add_i32 s73, 0, 0x1c000
	v_add_u32_e32 v156, s72, v164
	v_add_u32_e32 v171, s73, v164
	ds_read_b128 v[142:145], v156
	ds_read_b128 v[148:151], v156 offset:1024
	ds_read_b128 v[152:155], v156 offset:2048
	ds_read_b128 v[156:159], v156 offset:3072
	ds_read_b128 v[160:163], v171
	ds_read_b128 v[172:175], v171 offset:1024
	ds_read_b128 v[178:181], v171 offset:2048
	ds_read_b128 v[182:185], v171 offset:3072
	s_add_u32 s22, s38, 0x160000
	s_addc_u32 s23, s39, 0
	s_mov_b32 m0, s49
	ds_read_b128 v[186:189], v168 offset:32768
	ds_read_b128 v[190:193], v168 offset:33792
	ds_read_b128 v[194:197], v168 offset:34816
	ds_read_b128 v[198:201], v168 offset:35840
	ds_read_b128 v[202:205], v168 offset:36864
	ds_read_b128 v[206:209], v168 offset:37888
	ds_read_b128 v[210:213], v168 offset:38912
	ds_read_b128 v[214:217], v168 offset:39936
	global_load_lds_dwordx4 v130, s[22:23]
	s_mov_b32 m0, s50
	s_nop 0
	global_load_lds_dwordx4 v132, s[22:23]
	s_waitcnt vmcnt(8)
	s_waitcnt lgkmcnt(0)
	s_barrier
	s_setprio 1
	s_waitcnt lgkmcnt(0)
	v_mfma_f32_16x16x32_bf16 v[122:125], v[142:145], v[186:189], v[122:125]
	v_mfma_f32_16x16x32_bf16 v[126:129], v[152:155], v[186:189], v[126:129]
	v_mfma_f32_16x16x32_bf16 v[114:117], v[142:145], v[194:197], v[114:117]
	v_mfma_f32_16x16x32_bf16 v[118:121], v[152:155], v[194:197], v[118:121]
	v_mfma_f32_16x16x32_bf16 v[94:97], v[142:145], v[202:205], v[94:97]
	v_mfma_f32_16x16x32_bf16 v[90:93], v[152:155], v[202:205], v[90:93]
	v_mfma_f32_16x16x32_bf16 v[86:89], v[142:145], v[210:213], v[86:89]
	v_mfma_f32_16x16x32_bf16 v[82:85], v[152:155], v[210:213], v[82:85]
	v_mfma_f32_16x16x32_bf16 v[122:125], v[148:151], v[190:193], v[122:125]
	v_mfma_f32_16x16x32_bf16 v[126:129], v[156:159], v[190:193], v[126:129]
	v_mfma_f32_16x16x32_bf16 v[114:117], v[148:151], v[198:201], v[114:117]
	v_mfma_f32_16x16x32_bf16 v[118:121], v[156:159], v[198:201], v[118:121]
	v_mfma_f32_16x16x32_bf16 v[94:97], v[148:151], v[206:209], v[94:97]
	v_mfma_f32_16x16x32_bf16 v[90:93], v[156:159], v[206:209], v[90:93]
	v_mfma_f32_16x16x32_bf16 v[86:89], v[148:151], v[214:217], v[86:89]
	v_mfma_f32_16x16x32_bf16 v[82:85], v[156:159], v[214:217], v[82:85]
	s_setprio 0
	s_setprio 1
	v_mfma_f32_16x16x32_bf16 v[110:113], v[160:163], v[186:189], v[110:113]
	v_mfma_f32_16x16x32_bf16 v[106:109], v[178:181], v[186:189], v[106:109]
	v_mfma_f32_16x16x32_bf16 v[102:105], v[160:163], v[194:197], v[102:105]
	v_mfma_f32_16x16x32_bf16 v[98:101], v[178:181], v[194:197], v[98:101]
	v_mfma_f32_16x16x32_bf16 v[78:81], v[160:163], v[202:205], v[78:81]
	v_mfma_f32_16x16x32_bf16 v[74:77], v[178:181], v[202:205], v[74:77]
	v_mfma_f32_16x16x32_bf16 v[70:73], v[160:163], v[210:213], v[70:73]
	v_mfma_f32_16x16x32_bf16 v[66:69], v[178:181], v[210:213], v[66:69]
	v_mfma_f32_16x16x32_bf16 v[110:113], v[172:175], v[190:193], v[110:113]
	v_mfma_f32_16x16x32_bf16 v[106:109], v[182:185], v[190:193], v[106:109]
	v_mfma_f32_16x16x32_bf16 v[102:105], v[172:175], v[198:201], v[102:105]
	v_mfma_f32_16x16x32_bf16 v[98:101], v[182:185], v[198:201], v[98:101]
	v_mfma_f32_16x16x32_bf16 v[78:81], v[172:175], v[206:209], v[78:81]
	v_mfma_f32_16x16x32_bf16 v[74:77], v[182:185], v[206:209], v[74:77]
	v_mfma_f32_16x16x32_bf16 v[70:73], v[172:175], v[214:217], v[70:73]
	v_mfma_f32_16x16x32_bf16 v[66:69], v[182:185], v[214:217], v[66:69]
	s_setprio 0
	s_barrier
	s_add_i32 s22, s72, s44
	v_lshl_add_u64 v[218:219], v[218:219], 0, s[8:9]
	s_mov_b32 m0, s22
	ds_read_b128 v[186:189], v168 offset:49152
	ds_read_b128 v[190:193], v168 offset:50176
	ds_read_b128 v[194:197], v168 offset:51200
	ds_read_b128 v[198:201], v168 offset:52224
	ds_read_b128 v[202:205], v168 offset:53248
	ds_read_b128 v[206:209], v168 offset:54272
	ds_read_b128 v[210:213], v168 offset:55296
	ds_read_b128 v[214:217], v168 offset:56320
	global_load_lds_dwordx4 v[218:219], off
	s_add_i32 m0, s22, 0x2000
	s_add_u32 s22, s36, 0x160080
	v_lshl_add_u64 v[218:219], v[220:221], 0, s[8:9]
	s_addc_u32 s23, s37, 0
	s_add_i32 s36, s73, s44
	global_load_lds_dwordx4 v[218:219], off
	s_mov_b32 m0, s36
	s_nop 0
	global_load_lds_dwordx4 v130, s[22:23]
	s_add_i32 m0, s36, 0x2000
	s_nop 0
	global_load_lds_dwordx4 v132, s[22:23]
	v_lshl_add_u64 v[218:219], v[222:223], 0, s[8:9]
	s_mov_b32 m0, s52
	s_nop 0
	global_load_lds_dwordx4 v[218:219], off
	v_lshl_add_u64 v[218:219], v[224:225], 0, s[8:9]
	s_mov_b32 m0, s53
	s_nop 0
	global_load_lds_dwordx4 v[218:219], off
	s_waitcnt vmcnt(8)
	s_waitcnt lgkmcnt(0)
	s_barrier
	s_setprio 1
	s_waitcnt lgkmcnt(0)
	v_mfma_f32_16x16x32_bf16 v[62:65], v[142:145], v[186:189], v[62:65]
	v_mfma_f32_16x16x32_bf16 v[58:61], v[152:155], v[186:189], v[58:61]
	v_mfma_f32_16x16x32_bf16 v[54:57], v[142:145], v[194:197], v[54:57]
	v_mfma_f32_16x16x32_bf16 v[50:53], v[152:155], v[194:197], v[50:53]
	v_mfma_f32_16x16x32_bf16 v[30:33], v[142:145], v[202:205], v[30:33]
	v_mfma_f32_16x16x32_bf16 v[26:29], v[152:155], v[202:205], v[26:29]
	v_mfma_f32_16x16x32_bf16 v[22:25], v[142:145], v[210:213], v[22:25]
	v_mfma_f32_16x16x32_bf16 v[18:21], v[152:155], v[210:213], v[18:21]
	v_mfma_f32_16x16x32_bf16 v[62:65], v[148:151], v[190:193], v[62:65]
	v_mfma_f32_16x16x32_bf16 v[58:61], v[156:159], v[190:193], v[58:61]
	v_mfma_f32_16x16x32_bf16 v[54:57], v[148:151], v[198:201], v[54:57]
	v_mfma_f32_16x16x32_bf16 v[50:53], v[156:159], v[198:201], v[50:53]
	v_mfma_f32_16x16x32_bf16 v[30:33], v[148:151], v[206:209], v[30:33]
	v_mfma_f32_16x16x32_bf16 v[26:29], v[156:159], v[206:209], v[26:29]
	v_mfma_f32_16x16x32_bf16 v[22:25], v[148:151], v[214:217], v[22:25]
	v_mfma_f32_16x16x32_bf16 v[18:21], v[156:159], v[214:217], v[18:21]
	s_setprio 0
	s_setprio 1
	v_mfma_f32_16x16x32_bf16 v[46:49], v[160:163], v[186:189], v[46:49]
	v_mfma_f32_16x16x32_bf16 v[42:45], v[178:181], v[186:189], v[42:45]
	v_mfma_f32_16x16x32_bf16 v[38:41], v[160:163], v[194:197], v[38:41]
	v_mfma_f32_16x16x32_bf16 v[34:37], v[178:181], v[194:197], v[34:37]
	v_mfma_f32_16x16x32_bf16 v[14:17], v[160:163], v[202:205], v[14:17]
	v_mfma_f32_16x16x32_bf16 v[10:13], v[178:181], v[202:205], v[10:13]
	v_mfma_f32_16x16x32_bf16 v[6:9], v[160:163], v[210:213], v[6:9]
	v_mfma_f32_16x16x32_bf16 v[2:5], v[178:181], v[210:213], v[2:5]
	v_mfma_f32_16x16x32_bf16 v[46:49], v[172:175], v[190:193], v[46:49]
	v_mfma_f32_16x16x32_bf16 v[42:45], v[182:185], v[190:193], v[42:45]
	v_mfma_f32_16x16x32_bf16 v[38:41], v[172:175], v[198:201], v[38:41]
	v_mfma_f32_16x16x32_bf16 v[34:37], v[182:185], v[198:201], v[34:37]
	v_mfma_f32_16x16x32_bf16 v[14:17], v[172:175], v[206:209], v[14:17]
	v_mfma_f32_16x16x32_bf16 v[10:13], v[182:185], v[206:209], v[10:13]
	v_mfma_f32_16x16x32_bf16 v[6:9], v[172:175], v[214:217], v[6:9]
	v_mfma_f32_16x16x32_bf16 v[2:5], v[182:185], v[214:217], v[2:5]
	s_setprio 0
	s_barrier
	s_add_i32 s74, s74, 2
	s_add_u32 s67, s67, 0x100
	s_addc_u32 s69, s69, 0
	s_cmpk_gt_u32 s74, 0x55
	s_mov_b64 s[22:23], s[24:25]
	s_cbranch_scc0 .LBB0_1138
	s_and_b64 vcc, exec, s[10:11]
	s_cbranch_vccz .LBB0_1141
	s_barrier
